# SwiGLU epilogue: test the rstd cache before issuing the sum-of-squares loads; K-loop heads pinned to 8-byte phase 0
# baseline (speedup 1.0000x reference)
; #define PG8_STAGE(bufoff, gbase, voff) do { _Pragma("unroll") for (int _i = 0; _i < 2; ++_i) \
;         __builtin_amdgcn_global_load_lds((const unsigned*)((const char*)(gbase) + (voff)[_i]), (PG8_LAS unsigned*)(lds + (bufoff) + ldsw + _i * 8192), 16, 0, 0); } while (0)
; #define PG8_LDA(dst, b, h) do { _Pragma("unroll") for (int m = 0; m < 4; ++m) _Pragma("unroll") for (int k = 0; k < 2; ++k) dst[m][k] = *(const PG8_LAS bf16x8*)(lds + PG8_SA(b, h) + aoff + m * 2048 + k * 1024); } while (0)
; #define PG8_LDB(dst, b, h) do { _Pragma("unroll") for (int n = 0; n < 2; ++n) _Pragma("unroll") for (int k = 0; k < 2; ++k) dst[n][k] = *(const PG8_LAS bf16x8*)(lds + PG8_SB(b, h) + boff + n * 2048 + k * 1024); } while (0)
; #define PG8_MMA_NP(ai, bj, At, Bt) do { _Pragma("unroll") for (int m = 0; m < 4; ++m) _Pragma("unroll") for (int n = 0; n < 2; ++n) _Pragma("unroll") for (int k = 0; k < 2; ++k) \
;         acc[ai][bj][m][n] = __builtin_amdgcn_mfma_f32_16x16x32_bf16(Bt[n][k], At[m][k], acc[ai][bj][m][n], 0, 0, 0); } while (0)
; #define PG8_WAIT_V(n) asm volatile("s_waitcnt vmcnt(" #n ")" ::: "memory")
; #define PG8_WAIT_L(n) asm volatile("s_waitcnt lgkmcnt(" #n ")" ::: "memory")
; #define PG8_BAR __builtin_amdgcn_s_barrier()
; #define PG8_SCHED __builtin_amdgcn_sched_barrier(0)
; template <class Epi, class Sched, bool ALIGN_EPI = false, bool SP2 = false>
; __device__ __forceinline__ void gemm_phase(PG8_LAS unsigned char* lds, const Gemm g, const Sched& S, const Epi& E) {
;     ...
;             PG8_LDB(B0, 0, 0); PG8_LDB(B1, 0, 1); PG8_SCHED; PG8_LDA(At, 0, 0); PG8_STAGE(PG8_SA(1, 1), a1 + hstep, voffA);
;             PG8_WAIT_V(8); PG8_WAIT_L(0); PG8_BAR; __builtin_amdgcn_s_setprio(1); PG8_MMA_NP(0, 0, At, B0); PG8_MMA_NP(0, 1, At, B1); __builtin_amdgcn_s_setprio(0); PG8_BAR; PG8_SCHED;
;             PG8_LDA(At, 0, 1); PG8_STAGE(PG8_SB(0, 0), b2, voffB); PG8_STAGE(PG8_SB(0, 1), b2 + hstep, voffB); PG8_STAGE(PG8_SA(0, 0), a2, voffA);
;             PG8_WAIT_V(8); PG8_WAIT_L(0); PG8_BAR; __builtin_amdgcn_s_setprio(1); PG8_MMA_NP(1, 0, At, B0); PG8_MMA_NP(1, 1, At, B1); __builtin_amdgcn_s_setprio(0); PG8_BAR; PG8_SCHED;
.LBB0_165:
	s_ashr_i32 s47, s46, 31
	s_lshl_b64 s[14:15], s[46:47], 19
	s_add_u32 s50, s86, s14
	s_addc_u32 s51, s87, s15
	s_and_b64 s[14:15], s[40:41], exec
	s_cselect_b32 s47, s51, s3
	s_cselect_b32 s59, s50, s2
	s_ashr_i32 s45, s44, 31
	s_lshl_b64 s[14:15], s[44:45], 19
	v_readlane_b32 s22, v244, 18
	s_add_u32 s52, s22, s14
	v_readlane_b32 s14, v244, 19
	s_addc_u32 s53, s14, s15
	s_and_b64 s[14:15], s[40:41], exec
	s_cselect_b32 s45, s53, s13
	s_cselect_b32 s60, s52, s12
	s_add_u32 s2, s2, 0x40080
	s_addc_u32 s3, s3, 0
	s_add_u32 s61, s12, 0x100
	s_addc_u32 s62, s13, 0
	s_mov_b32 s63, -2
	s_add_u32 s12, s2, 0xfffc0080
	s_addc_u32 s13, s3, -1
	s_add_i32 s22, 0, 0x10000
	s_cmp_eq_u32 s63, 12
	s_cselect_b32 s15, s47, s13
	s_cselect_b32 s14, s59, s12
	s_cselect_b32 s13, s45, s62
	s_cselect_b32 s12, s60, s61
	s_add_i32 s23, 0, 0x14000
	v_add_u32_e32 v154, s22, v183
	v_add_u32_e32 v162, s23, v183
	ds_read_b128 v[130:133], v154
	ds_read_b128 v[146:149], v154 offset:1024
	ds_read_b128 v[150:153], v154 offset:2048
	ds_read_b128 v[154:157], v154 offset:3072
	ds_read_b128 v[158:161], v162
	ds_read_b128 v[178:181], v162 offset:1024
	ds_read_b128 v[186:189], v162 offset:2048
	ds_read_b128 v[202:205], v162 offset:3072
	v_lshl_add_u64 v[162:163], s[2:3], 0, v[142:143]
	s_add_i32 m0, s10, 0xc000
	ds_read_b128 v[206:209], v185
	ds_read_b128 v[210:213], v185 offset:1024
	ds_read_b128 v[214:217], v185 offset:2048
	ds_read_b128 v[218:221], v185 offset:3072
	ds_read_b128 v[222:225], v185 offset:4096
	ds_read_b128 v[226:229], v185 offset:5120
	ds_read_b128 v[230:233], v185 offset:6144
	ds_read_b128 v[234:237], v185 offset:7168
	global_load_lds_dwordx4 v[162:163], off
	v_lshl_add_u64 v[162:163], s[2:3], 0, v[144:145]
	s_add_i32 m0, s10, 0xe000
	s_nop 0
	global_load_lds_dwordx4 v[162:163], off
	s_waitcnt vmcnt(8)
	s_waitcnt lgkmcnt(0)
	s_barrier
	s_setprio 1
	s_waitcnt lgkmcnt(0)
	v_mfma_f32_16x16x32_bf16 v[126:129], v[130:133], v[206:209], 0
	v_mfma_f32_16x16x32_bf16 v[118:121], v[150:153], v[206:209], 0
	v_mfma_f32_16x16x32_bf16 v[110:113], v[130:133], v[214:217], 0
	v_mfma_f32_16x16x32_bf16 v[102:105], v[150:153], v[214:217], 0
	v_mfma_f32_16x16x32_bf16 v[94:97], v[130:133], v[222:225], 0
	v_mfma_f32_16x16x32_bf16 v[86:89], v[150:153], v[222:225], 0
	v_mfma_f32_16x16x32_bf16 v[78:81], v[130:133], v[230:233], 0
	v_mfma_f32_16x16x32_bf16 v[70:73], v[150:153], v[230:233], 0
	v_mfma_f32_16x16x32_bf16 v[122:125], v[158:161], v[206:209], 0
	v_mfma_f32_16x16x32_bf16 v[114:117], v[186:189], v[206:209], 0
	v_mfma_f32_16x16x32_bf16 v[106:109], v[158:161], v[214:217], 0
	v_mfma_f32_16x16x32_bf16 v[98:101], v[186:189], v[214:217], 0
	v_mfma_f32_16x16x32_bf16 v[90:93], v[158:161], v[222:225], 0
	v_mfma_f32_16x16x32_bf16 v[82:85], v[186:189], v[222:225], 0
	v_mfma_f32_16x16x32_bf16 v[74:77], v[158:161], v[230:233], 0
	v_mfma_f32_16x16x32_bf16 v[66:69], v[186:189], v[230:233], 0
	v_mfma_f32_16x16x32_bf16 v[126:129], v[146:149], v[210:213], v[126:129]
	v_mfma_f32_16x16x32_bf16 v[118:121], v[154:157], v[210:213], v[118:121]
	v_mfma_f32_16x16x32_bf16 v[110:113], v[146:149], v[218:221], v[110:113]
	v_mfma_f32_16x16x32_bf16 v[102:105], v[154:157], v[218:221], v[102:105]
	v_mfma_f32_16x16x32_bf16 v[94:97], v[146:149], v[226:229], v[94:97]
	v_mfma_f32_16x16x32_bf16 v[86:89], v[154:157], v[226:229], v[86:89]
	v_mfma_f32_16x16x32_bf16 v[78:81], v[146:149], v[234:237], v[78:81]
	v_mfma_f32_16x16x32_bf16 v[70:73], v[154:157], v[234:237], v[70:73]
	v_mfma_f32_16x16x32_bf16 v[122:125], v[178:181], v[210:213], v[122:125]
	v_mfma_f32_16x16x32_bf16 v[114:117], v[202:205], v[210:213], v[114:117]
	v_mfma_f32_16x16x32_bf16 v[106:109], v[178:181], v[218:221], v[106:109]
	v_mfma_f32_16x16x32_bf16 v[98:101], v[202:205], v[218:221], v[98:101]
	v_mfma_f32_16x16x32_bf16 v[90:93], v[178:181], v[226:229], v[90:93]
	v_mfma_f32_16x16x32_bf16 v[82:85], v[202:205], v[226:229], v[82:85]
	v_mfma_f32_16x16x32_bf16 v[74:77], v[178:181], v[234:237], v[74:77]
	v_mfma_f32_16x16x32_bf16 v[66:69], v[202:205], v[234:237], v[66:69]
	s_setprio 0
	s_barrier
	s_add_i32 s22, s22, s8
	v_lshl_add_u64 v[162:163], s[12:13], 0, v[0:1]
	s_mov_b32 m0, s22
	ds_read_b128 v[206:209], v185 offset:16384
	ds_read_b128 v[210:213], v185 offset:17408
	ds_read_b128 v[214:217], v185 offset:18432
	ds_read_b128 v[218:221], v185 offset:19456
	ds_read_b128 v[222:225], v185 offset:20480
	ds_read_b128 v[226:229], v185 offset:21504
	ds_read_b128 v[230:233], v185 offset:22528
	ds_read_b128 v[234:237], v185 offset:23552
	global_load_lds_dwordx4 v[162:163], off
	s_add_i32 m0, s22, 0x2000
	s_add_u32 s64, s12, 0x40000
	v_lshl_add_u64 v[190:191], s[12:13], 0, v[134:135]
	s_addc_u32 s65, s13, 0
	s_add_i32 s22, s23, s8
	global_load_lds_dwordx4 v[190:191], off
	v_lshl_add_u64 v[238:239], s[64:65], 0, v[0:1]
	s_mov_b32 m0, s22
	v_lshl_add_u64 v[240:241], s[14:15], 0, v[136:137]
	global_load_lds_dwordx4 v[238:239], off
	v_lshl_add_u64 v[238:239], s[64:65], 0, v[134:135]
	s_add_i32 m0, s22, 0x2000
	s_nop 0
	global_load_lds_dwordx4 v[238:239], off
	v_lshl_add_u64 v[238:239], s[14:15], 0, v[138:139]
	s_mov_b32 m0, s10
	s_nop 0
	global_load_lds_dwordx4 v[238:239], off
	s_mov_b32 m0, s29
	s_nop 0
	global_load_lds_dwordx4 v[240:241], off
	s_waitcnt vmcnt(8)
	s_waitcnt lgkmcnt(0)
	s_barrier
; #define PG8_STAGE(bufoff, gbase, voff) do { _Pragma("unroll") for (int _i = 0; _i < 2; ++_i) \
;         __builtin_amdgcn_global_load_lds((const unsigned*)((const char*)(gbase) + (voff)[_i]), (PG8_LAS unsigned*)(lds + (bufoff) + ldsw + _i * 8192), 16, 0, 0); } while (0)
; #define PG8_LDA(dst, b, h) do { _Pragma("unroll") for (int m = 0; m < 4; ++m) _Pragma("unroll") for (int k = 0; k < 2; ++k) dst[m][k] = *(const PG8_LAS bf16x8*)(lds + PG8_SA(b, h) + aoff + m * 2048 + k * 1024); } while (0)
; #define PG8_LDB(dst, b, h) do { _Pragma("unroll") for (int n = 0; n < 2; ++n) _Pragma("unroll") for (int k = 0; k < 2; ++k) dst[n][k] = *(const PG8_LAS bf16x8*)(lds + PG8_SB(b, h) + boff + n * 2048 + k * 1024); } while (0)
; #define PG8_MMA_NP(ai, bj, At, Bt) do { _Pragma("unroll") for (int m = 0; m < 4; ++m) _Pragma("unroll") for (int n = 0; n < 2; ++n) _Pragma("unroll") for (int k = 0; k < 2; ++k) \
;         acc[ai][bj][m][n] = __builtin_amdgcn_mfma_f32_16x16x32_bf16(Bt[n][k], At[m][k], acc[ai][bj][m][n], 0, 0, 0); } while (0)
; #define PG8_WAIT_V(n) asm volatile("s_waitcnt vmcnt(" #n ")" ::: "memory")
; #define PG8_WAIT_L(n) asm volatile("s_waitcnt lgkmcnt(" #n ")" ::: "memory")
; #define PG8_BAR __builtin_amdgcn_s_barrier()
; #define PG8_SCHED __builtin_amdgcn_sched_barrier(0)
; template <class Epi, class Sched, bool ALIGN_EPI = false, bool SP2 = false>
; __device__ __forceinline__ void gemm_phase(PG8_LAS unsigned char* lds, const Gemm g, const Sched& S, const Epi& E) {
;     ...
;             PG8_WAIT_V(8); PG8_WAIT_L(0); PG8_BAR; __builtin_amdgcn_s_setprio(1); PG8_MMA_NP(1, 0, At, B0); PG8_MMA_NP(1, 1, At, B1); __builtin_amdgcn_s_setprio(0); PG8_BAR; PG8_SCHED;
;             PG8_LDB(B0, 1, 0); PG8_LDB(B1, 1, 1); PG8_SCHED; PG8_LDA(At, 1, 0); PG8_STAGE(PG8_SA(0, 1), a2 + hstep, voffA);
;             PG8_WAIT_V(8); PG8_WAIT_L(0); PG8_BAR; __builtin_amdgcn_s_setprio(1); PG8_MMA_NP(0, 0, At, B0); PG8_MMA_NP(0, 1, At, B1); __builtin_amdgcn_s_setprio(0); PG8_BAR; PG8_SCHED;
;             PG8_LDA(At, 1, 1); PG8_STAGE(PG8_SB(1, 0), b3, voffB); PG8_STAGE(PG8_SB(1, 1), b3 + hstep, voffB); PG8_STAGE(PG8_SA(1, 0), a3, voffA);
	s_setprio 1
	s_waitcnt lgkmcnt(0)
	v_mfma_f32_16x16x32_bf16 v[62:65], v[130:133], v[206:209], 0
	v_mfma_f32_16x16x32_bf16 v[54:57], v[150:153], v[206:209], 0
	v_mfma_f32_16x16x32_bf16 v[46:49], v[130:133], v[214:217], 0
	v_mfma_f32_16x16x32_bf16 v[38:41], v[150:153], v[214:217], 0
	v_mfma_f32_16x16x32_bf16 v[30:33], v[130:133], v[222:225], 0
	v_mfma_f32_16x16x32_bf16 v[22:25], v[150:153], v[222:225], 0
	v_mfma_f32_16x16x32_bf16 v[14:17], v[130:133], v[230:233], 0
	v_mfma_f32_16x16x32_bf16 v[6:9], v[150:153], v[230:233], 0
	v_mfma_f32_16x16x32_bf16 v[58:61], v[158:161], v[206:209], 0
	v_mfma_f32_16x16x32_bf16 v[50:53], v[186:189], v[206:209], 0
	v_mfma_f32_16x16x32_bf16 v[42:45], v[158:161], v[214:217], 0
	v_mfma_f32_16x16x32_bf16 v[34:37], v[186:189], v[214:217], 0
	v_mfma_f32_16x16x32_bf16 v[26:29], v[158:161], v[222:225], 0
	v_mfma_f32_16x16x32_bf16 v[18:21], v[186:189], v[222:225], 0
	v_mfma_f32_16x16x32_bf16 v[10:13], v[158:161], v[230:233], 0
	v_mfma_f32_16x16x32_bf16 v[2:5], v[186:189], v[230:233], 0
	v_mfma_f32_16x16x32_bf16 v[62:65], v[146:149], v[210:213], v[62:65]
	v_mfma_f32_16x16x32_bf16 v[54:57], v[154:157], v[210:213], v[54:57]
	v_mfma_f32_16x16x32_bf16 v[46:49], v[146:149], v[218:221], v[46:49]
	v_mfma_f32_16x16x32_bf16 v[38:41], v[154:157], v[218:221], v[38:41]
	v_mfma_f32_16x16x32_bf16 v[30:33], v[146:149], v[226:229], v[30:33]
	v_mfma_f32_16x16x32_bf16 v[22:25], v[154:157], v[226:229], v[22:25]
	v_mfma_f32_16x16x32_bf16 v[14:17], v[146:149], v[234:237], v[14:17]
	v_mfma_f32_16x16x32_bf16 v[6:9], v[154:157], v[234:237], v[6:9]
	v_mfma_f32_16x16x32_bf16 v[58:61], v[178:181], v[210:213], v[58:61]
	v_mfma_f32_16x16x32_bf16 v[50:53], v[202:205], v[210:213], v[50:53]
	v_mfma_f32_16x16x32_bf16 v[42:45], v[178:181], v[218:221], v[42:45]
	v_mfma_f32_16x16x32_bf16 v[34:37], v[202:205], v[218:221], v[34:37]
	v_mfma_f32_16x16x32_bf16 v[26:29], v[178:181], v[226:229], v[26:29]
	v_mfma_f32_16x16x32_bf16 v[18:21], v[202:205], v[226:229], v[18:21]
	v_mfma_f32_16x16x32_bf16 v[10:13], v[178:181], v[234:237], v[10:13]
	v_mfma_f32_16x16x32_bf16 v[2:5], v[202:205], v[234:237], v[2:5]
	s_setprio 0
	s_barrier
	s_add_i32 s22, 0, 0x18000
	s_add_i32 s23, 0, 0x1c000
	v_add_u32_e32 v154, s22, v183
	v_add_u32_e32 v202, s23, v183
	ds_read_b128 v[130:133], v154
	ds_read_b128 v[146:149], v154 offset:1024
	ds_read_b128 v[150:153], v154 offset:2048
	ds_read_b128 v[154:157], v154 offset:3072
	ds_read_b128 v[158:161], v202
	ds_read_b128 v[178:181], v202 offset:1024
	ds_read_b128 v[186:189], v202 offset:2048
	ds_read_b128 v[202:205], v202 offset:3072
	s_add_u32 s14, s14, 0x40000
	s_addc_u32 s15, s15, 0
	s_mov_b32 m0, s30
	v_lshl_add_u64 v[242:243], s[14:15], 0, v[138:139]
	ds_read_b128 v[206:209], v185 offset:32768
	ds_read_b128 v[210:213], v185 offset:33792
	ds_read_b128 v[214:217], v185 offset:34816
	ds_read_b128 v[218:221], v185 offset:35840
	ds_read_b128 v[222:225], v185 offset:36864
	ds_read_b128 v[226:229], v185 offset:37888
	ds_read_b128 v[230:233], v185 offset:38912
	ds_read_b128 v[234:237], v185 offset:39936
	global_load_lds_dwordx4 v[242:243], off
	v_lshl_add_u64 v[242:243], s[14:15], 0, v[136:137]
	s_mov_b32 m0, s31
	s_nop 0
	global_load_lds_dwordx4 v[242:243], off
	s_waitcnt vmcnt(8)
	s_waitcnt lgkmcnt(0)
	s_barrier
	s_setprio 1
	s_waitcnt lgkmcnt(0)
	v_mfma_f32_16x16x32_bf16 v[126:129], v[130:133], v[206:209], v[126:129]
	v_mfma_f32_16x16x32_bf16 v[118:121], v[150:153], v[206:209], v[118:121]
	v_mfma_f32_16x16x32_bf16 v[110:113], v[130:133], v[214:217], v[110:113]
	v_mfma_f32_16x16x32_bf16 v[102:105], v[150:153], v[214:217], v[102:105]
	v_mfma_f32_16x16x32_bf16 v[94:97], v[130:133], v[222:225], v[94:97]
	v_mfma_f32_16x16x32_bf16 v[86:89], v[150:153], v[222:225], v[86:89]
	v_mfma_f32_16x16x32_bf16 v[78:81], v[130:133], v[230:233], v[78:81]
	v_mfma_f32_16x16x32_bf16 v[70:73], v[150:153], v[230:233], v[70:73]
	v_mfma_f32_16x16x32_bf16 v[122:125], v[158:161], v[206:209], v[122:125]
	v_mfma_f32_16x16x32_bf16 v[114:117], v[186:189], v[206:209], v[114:117]
	v_mfma_f32_16x16x32_bf16 v[106:109], v[158:161], v[214:217], v[106:109]
	v_mfma_f32_16x16x32_bf16 v[98:101], v[186:189], v[214:217], v[98:101]
	v_mfma_f32_16x16x32_bf16 v[90:93], v[158:161], v[222:225], v[90:93]
	v_mfma_f32_16x16x32_bf16 v[82:85], v[186:189], v[222:225], v[82:85]
	v_mfma_f32_16x16x32_bf16 v[74:77], v[158:161], v[230:233], v[74:77]
	v_mfma_f32_16x16x32_bf16 v[66:69], v[186:189], v[230:233], v[66:69]
	v_mfma_f32_16x16x32_bf16 v[126:129], v[146:149], v[210:213], v[126:129]
	v_mfma_f32_16x16x32_bf16 v[118:121], v[154:157], v[210:213], v[118:121]
	v_mfma_f32_16x16x32_bf16 v[110:113], v[146:149], v[218:221], v[110:113]
	v_mfma_f32_16x16x32_bf16 v[102:105], v[154:157], v[218:221], v[102:105]
	v_mfma_f32_16x16x32_bf16 v[94:97], v[146:149], v[226:229], v[94:97]
	v_mfma_f32_16x16x32_bf16 v[86:89], v[154:157], v[226:229], v[86:89]
	v_mfma_f32_16x16x32_bf16 v[78:81], v[146:149], v[234:237], v[78:81]
	v_mfma_f32_16x16x32_bf16 v[70:73], v[154:157], v[234:237], v[70:73]
	v_mfma_f32_16x16x32_bf16 v[122:125], v[178:181], v[210:213], v[122:125]
	v_mfma_f32_16x16x32_bf16 v[114:117], v[202:205], v[210:213], v[114:117]
	v_mfma_f32_16x16x32_bf16 v[106:109], v[178:181], v[218:221], v[106:109]
	v_mfma_f32_16x16x32_bf16 v[98:101], v[202:205], v[218:221], v[98:101]
	v_mfma_f32_16x16x32_bf16 v[90:93], v[178:181], v[226:229], v[90:93]
	v_mfma_f32_16x16x32_bf16 v[82:85], v[202:205], v[226:229], v[82:85]
	v_mfma_f32_16x16x32_bf16 v[74:77], v[178:181], v[234:237], v[74:77]
	v_mfma_f32_16x16x32_bf16 v[66:69], v[202:205], v[234:237], v[66:69]
	s_setprio 0
	s_barrier
; #define PG8_STAGE(bufoff, gbase, voff) do { _Pragma("unroll") for (int _i = 0; _i < 2; ++_i) \
;         __builtin_amdgcn_global_load_lds((const unsigned*)((const char*)(gbase) + (voff)[_i]), (PG8_LAS unsigned*)(lds + (bufoff) + ldsw + _i * 8192), 16, 0, 0); } while (0)
; #define PG8_LDA(dst, b, h) do { _Pragma("unroll") for (int m = 0; m < 4; ++m) _Pragma("unroll") for (int k = 0; k < 2; ++k) dst[m][k] = *(const PG8_LAS bf16x8*)(lds + PG8_SA(b, h) + aoff + m * 2048 + k * 1024); } while (0)
; #define PG8_MMA_NP(ai, bj, At, Bt) do { _Pragma("unroll") for (int m = 0; m < 4; ++m) _Pragma("unroll") for (int n = 0; n < 2; ++n) _Pragma("unroll") for (int k = 0; k < 2; ++k) \
;         acc[ai][bj][m][n] = __builtin_amdgcn_mfma_f32_16x16x32_bf16(Bt[n][k], At[m][k], acc[ai][bj][m][n], 0, 0, 0); } while (0)
; #define PG8_WAIT_V(n) asm volatile("s_waitcnt vmcnt(" #n ")" ::: "memory")
; #define PG8_WAIT_L(n) asm volatile("s_waitcnt lgkmcnt(" #n ")" ::: "memory")
; #define PG8_BAR __builtin_amdgcn_s_barrier()
; #define PG8_SCHED __builtin_amdgcn_sched_barrier(0)
; template <class Epi, class Sched, bool ALIGN_EPI = false, bool SP2 = false>
; __device__ __forceinline__ void gemm_phase(PG8_LAS unsigned char* lds, const Gemm g, const Sched& S, const Epi& E) {
;     ...
;             PG8_LDA(At, 1, 1); PG8_STAGE(PG8_SB(1, 0), b3, voffB); PG8_STAGE(PG8_SB(1, 1), b3 + hstep, voffB); PG8_STAGE(PG8_SA(1, 0), a3, voffA);
;             PG8_WAIT_V(8); PG8_WAIT_L(0); PG8_BAR; __builtin_amdgcn_s_setprio(1); PG8_MMA_NP(1, 0, At, B0); PG8_MMA_NP(1, 1, At, B1); __builtin_amdgcn_s_setprio(0); PG8_BAR; PG8_SCHED;
	s_add_i32 s14, s22, s8
	v_lshl_add_u64 v[162:163], v[162:163], 0, s[20:21]
	s_mov_b32 m0, s14
	ds_read_b128 v[206:209], v185 offset:49152
	ds_read_b128 v[210:213], v185 offset:50176
	ds_read_b128 v[214:217], v185 offset:51200
	ds_read_b128 v[218:221], v185 offset:52224
	ds_read_b128 v[222:225], v185 offset:53248
	ds_read_b128 v[226:229], v185 offset:54272
	ds_read_b128 v[230:233], v185 offset:55296
	ds_read_b128 v[234:237], v185 offset:56320
	global_load_lds_dwordx4 v[162:163], off
	s_add_i32 m0, s14, 0x2000
	s_add_u32 s12, s12, 0x40080
	v_lshl_add_u64 v[162:163], v[190:191], 0, s[20:21]
	s_addc_u32 s13, s13, 0
	s_add_i32 s14, s23, s8
	global_load_lds_dwordx4 v[162:163], off
	v_lshl_add_u64 v[162:163], s[12:13], 0, v[0:1]
	s_mov_b32 m0, s14
	s_nop 0
	global_load_lds_dwordx4 v[162:163], off
	v_lshl_add_u64 v[162:163], s[12:13], 0, v[134:135]
	s_add_i32 m0, s14, 0x2000
	s_nop 0
	global_load_lds_dwordx4 v[162:163], off
	v_lshl_add_u64 v[162:163], v[238:239], 0, s[20:21]
	s_mov_b32 m0, s54
	s_nop 0
	global_load_lds_dwordx4 v[162:163], off
	v_lshl_add_u64 v[162:163], v[240:241], 0, s[20:21]
	s_mov_b32 m0, s55
	s_nop 0
	global_load_lds_dwordx4 v[162:163], off
	s_waitcnt vmcnt(8)
	s_waitcnt lgkmcnt(0)
	s_barrier
	s_setprio 1
	s_waitcnt lgkmcnt(0)
	v_mfma_f32_16x16x32_bf16 v[62:65], v[130:133], v[206:209], v[62:65]
	v_mfma_f32_16x16x32_bf16 v[54:57], v[150:153], v[206:209], v[54:57]
	v_mfma_f32_16x16x32_bf16 v[46:49], v[130:133], v[214:217], v[46:49]
	v_mfma_f32_16x16x32_bf16 v[38:41], v[150:153], v[214:217], v[38:41]
	v_mfma_f32_16x16x32_bf16 v[30:33], v[130:133], v[222:225], v[30:33]
	v_mfma_f32_16x16x32_bf16 v[22:25], v[150:153], v[222:225], v[22:25]
	v_mfma_f32_16x16x32_bf16 v[14:17], v[130:133], v[230:233], v[14:17]
	v_mfma_f32_16x16x32_bf16 v[6:9], v[150:153], v[230:233], v[6:9]
	v_mfma_f32_16x16x32_bf16 v[58:61], v[158:161], v[206:209], v[58:61]
	v_mfma_f32_16x16x32_bf16 v[50:53], v[186:189], v[206:209], v[50:53]
	v_mfma_f32_16x16x32_bf16 v[42:45], v[158:161], v[214:217], v[42:45]
	v_mfma_f32_16x16x32_bf16 v[34:37], v[186:189], v[214:217], v[34:37]
	v_mfma_f32_16x16x32_bf16 v[26:29], v[158:161], v[222:225], v[26:29]
	v_mfma_f32_16x16x32_bf16 v[18:21], v[186:189], v[222:225], v[18:21]
	v_mfma_f32_16x16x32_bf16 v[10:13], v[158:161], v[230:233], v[10:13]
	v_mfma_f32_16x16x32_bf16 v[2:5], v[186:189], v[230:233], v[2:5]
	v_mfma_f32_16x16x32_bf16 v[62:65], v[146:149], v[210:213], v[62:65]
	v_mfma_f32_16x16x32_bf16 v[54:57], v[154:157], v[210:213], v[54:57]
	v_mfma_f32_16x16x32_bf16 v[46:49], v[146:149], v[218:221], v[46:49]
	v_mfma_f32_16x16x32_bf16 v[38:41], v[154:157], v[218:221], v[38:41]
	v_mfma_f32_16x16x32_bf16 v[30:33], v[146:149], v[226:229], v[30:33]
	v_mfma_f32_16x16x32_bf16 v[22:25], v[154:157], v[226:229], v[22:25]
	v_mfma_f32_16x16x32_bf16 v[14:17], v[146:149], v[234:237], v[14:17]
	v_mfma_f32_16x16x32_bf16 v[6:9], v[154:157], v[234:237], v[6:9]
	v_mfma_f32_16x16x32_bf16 v[58:61], v[178:181], v[210:213], v[58:61]
	v_mfma_f32_16x16x32_bf16 v[50:53], v[202:205], v[210:213], v[50:53]
	v_mfma_f32_16x16x32_bf16 v[42:45], v[178:181], v[218:221], v[42:45]
	v_mfma_f32_16x16x32_bf16 v[34:37], v[202:205], v[218:221], v[34:37]
	v_mfma_f32_16x16x32_bf16 v[26:29], v[178:181], v[226:229], v[26:29]
	v_mfma_f32_16x16x32_bf16 v[18:21], v[202:205], v[226:229], v[18:21]
	v_mfma_f32_16x16x32_bf16 v[10:13], v[178:181], v[234:237], v[10:13]
	v_mfma_f32_16x16x32_bf16 v[2:5], v[202:205], v[234:237], v[2:5]
	s_setprio 0
	s_barrier
	s_add_i32 s63, s63, 2
	s_add_u32 s2, s2, 0x100
	s_addc_u32 s3, s3, 0
	s_add_u32 s61, s61, 0x100
	s_addc_u32 s62, s62, 0
	s_cmp_gt_u32 s63, 13
	s_cbranch_scc0 .LBB0_166
	s_branch .Lkexit_0
	.p2align 3

; DI void row_rstd(const float* ssq, int row0, int fq, float (&rs)[2][4]) {
; #pragma unroll
;     for (int ai = 0; ai < 2; ++ai)
; #pragma unroll
;         for (int m = 0; m < 4; ++m) {
;             const f32x4 v = *(const f32x4*)(ssq + (size_t)(row0 + ai * 128 + m * 16) * 16 + 4 * fq);
;             float s = (v[0] + v[1]) + (v[2] + v[3]);
;             s += __shfl_xor(s, 16); s += __shfl_xor(s, 32);
;             rs[ai][m] = rsqrtf(s * (1.0f / DM) + EPS);
;         }
; }
.Lkexit_0:
	s_cmp_eq_u32 s58, s98
	s_cbranch_scc1 .Lrc_skip_0
	v_lshl_add_u32 v234, s58, 8, v182
	v_ashrrev_i32_e32 v235, 31, v234
	v_add_u32_e32 v236, 0x80, v234
	v_ashrrev_i32_e32 v237, 31, v236
	v_lshlrev_b64 v[234:235], 6, v[234:235]
	v_lshlrev_b64 v[236:237], 6, v[236:237]
	v_lshl_add_u64 v[234:235], v[140:141], 0, v[234:235]
	v_lshl_add_u64 v[236:237], v[140:141], 0, v[236:237]
	global_load_dwordx4 v[202:205], v[234:235], off
	global_load_dwordx4 v[206:209], v[234:235], off offset:1024
	global_load_dwordx4 v[210:213], v[234:235], off offset:2048
	global_load_dwordx4 v[214:217], v[234:235], off offset:3072
	global_load_dwordx4 v[218:221], v[236:237], off
	global_load_dwordx4 v[222:225], v[236:237], off offset:1024
	global_load_dwordx4 v[226:229], v[236:237], off offset:2048
	global_load_dwordx4 v[230:233], v[236:237], off offset:3072
.Lrc_skip_0:
	s_and_b64 vcc, exec, s[42:43]
	s_cbranch_vccz .LBB0_169
	s_barrier

;     DI void operator()(const f32x4 (&acc)[2][2][4][2], const pg8::Unit& u, int wr, int wc, int fr, int fq) const {
;     ...
;         float rs[2][4]; row_rstd(ssq, row0, fq, rs);
; #pragma unroll
;         for (int ai = 0; ai < 2; ++ai)
; #pragma unroll
;             for (int m = 0; m < 4; ++m) {
;                 typedef float f32x2 __attribute__((ext_vector_type(2)));
;                 const float r = rs[ai][m]; const float r2s = r * r, rls = r * -1.44269504f; const f32x2 r2 = {r2s, r2s}, rl = {rls, rls};
.Lrc_hit_0:
	v_add_u32_e32 v148, 0xa0, v160
	v_ashrrev_i32_e32 v149, 31, v148
	v_accvgpr_read_b32 v161, a0
	v_accvgpr_read_b32 v159, a1
	v_accvgpr_read_b32 v157, a2
	v_accvgpr_read_b32 v155, a3
	v_accvgpr_read_b32 v153, a4
	v_accvgpr_read_b32 v151, a5
	v_add_u32_e32 v146, 0xb0, v160
	v_ashrrev_i32_e32 v147, 31, v146
	v_ashrrev_i32_e32 v163, 31, v162
	v_accvgpr_read_b32 v131, a6
	v_accvgpr_read_b32 v130, a7

; template <class Epi, class Sched, bool ALIGN_EPI = false, bool SP2 = false>
; __device__ __forceinline__ void gemm_phase(PG8_LAS unsigned char* lds, const Gemm g, const Sched& S, const Epi& E) {
;     ...
; #pragma unroll
;         for (int a = 0; a < 2; ++a)
; #pragma unroll
;             for (int b = 0; b < 2; ++b)
; #pragma unroll
;                 for (int m = 0; m < 4; ++m)
; #pragma unroll
;                     for (int n = 0; n < 2; ++n) acc[a][b][m][n] = (f32x4){0.f, 0.f, 0.f, 0.f};
;         cur = nxt; cA = nA; cB = nB; ++ui;
.LBB0_193:
	s_add_u32 s59, s40, 0x100
	v_mov_b32_e32 v2, 0
	s_addc_u32 s69, s41, 0
	s_mov_b32 s70, -2
	s_waitcnt lgkmcnt(0)
	v_mov_b32_e32 v3, v2
	v_mov_b32_e32 v4, v2
	v_mov_b32_e32 v5, v2
	v_mov_b32_e32 v6, v2
	v_mov_b32_e32 v7, v2
	v_mov_b32_e32 v8, v2
	v_mov_b32_e32 v9, v2
	v_mov_b32_e32 v18, v2
	v_mov_b32_e32 v19, v2
	v_mov_b32_e32 v20, v2
	v_mov_b32_e32 v21, v2
	v_mov_b32_e32 v22, v2
	v_mov_b32_e32 v23, v2
	v_mov_b32_e32 v24, v2
	v_mov_b32_e32 v25, v2
	v_mov_b32_e32 v34, v2
	v_mov_b32_e32 v35, v2
	v_mov_b32_e32 v36, v2
	v_mov_b32_e32 v37, v2
	v_mov_b32_e32 v38, v2
	v_mov_b32_e32 v39, v2
	v_mov_b32_e32 v40, v2
	v_mov_b32_e32 v41, v2
	v_mov_b32_e32 v50, v2
	v_mov_b32_e32 v51, v2
	v_mov_b32_e32 v52, v2
	v_mov_b32_e32 v53, v2
	v_mov_b32_e32 v54, v2
	v_mov_b32_e32 v55, v2
	v_mov_b32_e32 v56, v2
	v_mov_b32_e32 v57, v2
	v_mov_b32_e32 v10, v2
	v_mov_b32_e32 v11, v2
	v_mov_b32_e32 v12, v2
	v_mov_b32_e32 v13, v2
	v_mov_b32_e32 v14, v2
	v_mov_b32_e32 v15, v2
	v_mov_b32_e32 v16, v2
	v_mov_b32_e32 v17, v2
	v_mov_b32_e32 v26, v2
	v_mov_b32_e32 v27, v2
	v_mov_b32_e32 v28, v2
	v_mov_b32_e32 v29, v2
	v_mov_b32_e32 v30, v2
	v_mov_b32_e32 v31, v2
	v_mov_b32_e32 v32, v2
	v_mov_b32_e32 v33, v2
	v_mov_b32_e32 v42, v2
	v_mov_b32_e32 v43, v2
	v_mov_b32_e32 v44, v2
	v_mov_b32_e32 v45, v2
	v_mov_b32_e32 v46, v2
	v_mov_b32_e32 v47, v2
	v_mov_b32_e32 v48, v2
	v_mov_b32_e32 v49, v2
	v_mov_b32_e32 v58, v2
	v_mov_b32_e32 v59, v2
	v_mov_b32_e32 v60, v2
	v_mov_b32_e32 v61, v2
	v_mov_b32_e32 v62, v2
	v_mov_b32_e32 v63, v2
	v_mov_b32_e32 v64, v2
	v_mov_b32_e32 v65, v2
	v_mov_b32_e32 v66, v2
	v_mov_b32_e32 v67, v2
	v_mov_b32_e32 v68, v2
	v_mov_b32_e32 v69, v2
	v_mov_b32_e32 v70, v2
	v_mov_b32_e32 v71, v2
	v_mov_b32_e32 v72, v2
	v_mov_b32_e32 v73, v2
	v_mov_b32_e32 v82, v2
	v_mov_b32_e32 v83, v2
	v_mov_b32_e32 v84, v2
	v_mov_b32_e32 v85, v2
	v_mov_b32_e32 v86, v2
	v_mov_b32_e32 v87, v2
	v_mov_b32_e32 v88, v2
	v_mov_b32_e32 v89, v2
	v_mov_b32_e32 v98, v2
	v_mov_b32_e32 v99, v2
	v_mov_b32_e32 v100, v2
	v_mov_b32_e32 v101, v2
	v_mov_b32_e32 v102, v2
	v_mov_b32_e32 v103, v2
	v_mov_b32_e32 v104, v2
	v_mov_b32_e32 v105, v2
	v_mov_b32_e32 v114, v2
	v_mov_b32_e32 v115, v2
	v_mov_b32_e32 v116, v2
	v_mov_b32_e32 v117, v2
	v_mov_b32_e32 v118, v2
	v_mov_b32_e32 v119, v2
	v_mov_b32_e32 v120, v2
	v_mov_b32_e32 v121, v2
	v_mov_b32_e32 v74, v2
	v_mov_b32_e32 v75, v2
	v_mov_b32_e32 v76, v2
	v_mov_b32_e32 v77, v2
	v_mov_b32_e32 v78, v2
	v_mov_b32_e32 v79, v2
	v_mov_b32_e32 v80, v2
	v_mov_b32_e32 v81, v2
	v_mov_b32_e32 v90, v2
	v_mov_b32_e32 v91, v2
	v_mov_b32_e32 v92, v2
	v_mov_b32_e32 v93, v2
	v_mov_b32_e32 v94, v2
	v_mov_b32_e32 v95, v2
	v_mov_b32_e32 v96, v2
	v_mov_b32_e32 v97, v2
	v_mov_b32_e32 v106, v2
	v_mov_b32_e32 v107, v2
	v_mov_b32_e32 v108, v2
	v_mov_b32_e32 v109, v2
	v_mov_b32_e32 v110, v2
	v_mov_b32_e32 v111, v2
	v_mov_b32_e32 v112, v2
	v_mov_b32_e32 v113, v2
	v_mov_b32_e32 v122, v2
	v_mov_b32_e32 v123, v2
	v_mov_b32_e32 v124, v2
	v_mov_b32_e32 v125, v2
	v_mov_b32_e32 v126, v2
	v_mov_b32_e32 v127, v2
	v_mov_b32_e32 v128, v2
	v_mov_b32_e32 v129, v2
	.p2align 3

; #define PG8_STAGE(bufoff, gbase, voff) do { _Pragma("unroll") for (int _i = 0; _i < 2; ++_i) \
;         __builtin_amdgcn_global_load_lds((const unsigned*)((const char*)(gbase) + (voff)[_i]), (PG8_LAS unsigned*)(lds + (bufoff) + ldsw + _i * 8192), 16, 0, 0); } while (0)
; #define PG8_LDA(dst, b, h) do { _Pragma("unroll") for (int m = 0; m < 4; ++m) _Pragma("unroll") for (int k = 0; k < 2; ++k) dst[m][k] = *(const PG8_LAS bf16x8*)(lds + PG8_SA(b, h) + aoff + m * 2048 + k * 1024); } while (0)
; #define PG8_LDB(dst, b, h) do { _Pragma("unroll") for (int n = 0; n < 2; ++n) _Pragma("unroll") for (int k = 0; k < 2; ++k) dst[n][k] = *(const PG8_LAS bf16x8*)(lds + PG8_SB(b, h) + boff + n * 2048 + k * 1024); } while (0)
; #define PG8_MMA_NP(ai, bj, At, Bt) do { _Pragma("unroll") for (int m = 0; m < 4; ++m) _Pragma("unroll") for (int n = 0; n < 2; ++n) _Pragma("unroll") for (int k = 0; k < 2; ++k) \
;         acc[ai][bj][m][n] = __builtin_amdgcn_mfma_f32_16x16x32_bf16(Bt[n][k], At[m][k], acc[ai][bj][m][n], 0, 0, 0); } while (0)
; #define PG8_WAIT_V(n) asm volatile("s_waitcnt vmcnt(" #n ")" ::: "memory")
; #define PG8_WAIT_L(n) asm volatile("s_waitcnt lgkmcnt(" #n ")" ::: "memory")
; #define PG8_BAR __builtin_amdgcn_s_barrier()
; #define PG8_SCHED __builtin_amdgcn_sched_barrier(0)
; template <class Epi, class Sched, bool ALIGN_EPI = false, bool SP2 = false>
; __device__ __forceinline__ void gemm_phase(PG8_LAS unsigned char* lds, const Gemm g, const Sched& S, const Epi& E) {
;     ...
;             PG8_LDB(B0, 0, 0); PG8_LDB(B1, 0, 1); PG8_SCHED; PG8_LDA(At, 0, 0); PG8_STAGE(PG8_SA(1, 1), a1 + hstep, voffA);
;             PG8_WAIT_V(8); PG8_WAIT_L(0); PG8_BAR; __builtin_amdgcn_s_setprio(1); PG8_MMA_NP(0, 0, At, B0); PG8_MMA_NP(0, 1, At, B1); __builtin_amdgcn_s_setprio(0); PG8_BAR; PG8_SCHED;
;             PG8_LDA(At, 0, 1); PG8_STAGE(PG8_SB(0, 0), b2, voffB); PG8_STAGE(PG8_SB(0, 1), b2 + hstep, voffB); PG8_STAGE(PG8_SA(0, 0), a2, voffA);
;             PG8_WAIT_V(8); PG8_WAIT_L(0); PG8_BAR; __builtin_amdgcn_s_setprio(1); PG8_MMA_NP(1, 0, At, B0); PG8_MMA_NP(1, 1, At, B1); __builtin_amdgcn_s_setprio(0); PG8_BAR; PG8_SCHED;
.LBB0_369:
	s_ashr_i32 s55, s54, 31
	s_lshl_b64 s[40:41], s[54:55], 19
	s_add_u32 s56, s86, s40
	s_addc_u32 s57, s87, s41
	s_and_b64 s[40:41], s[42:43], exec
	s_cselect_b32 s46, s57, s13
	s_cselect_b32 s47, s56, s12
	s_ashr_i32 s53, s52, 31
	s_lshl_b64 s[40:41], s[52:53], 19
	s_add_u32 s58, s8, s40
	s_addc_u32 s59, s10, s41
	s_and_b64 s[40:41], s[42:43], exec
	s_cselect_b32 s48, s59, s15
	s_cselect_b32 s49, s58, s14
	s_add_u32 s12, s12, 0x40080
	s_addc_u32 s13, s13, 0
	s_add_u32 s53, s14, 0x100
	s_addc_u32 s55, s15, 0
	s_mov_b32 s65, -2
	s_add_u32 s14, s12, 0xfffc0080
	s_addc_u32 s15, s13, -1
	s_add_i32 s22, 0, 0x10000
	s_cmp_eq_u32 s65, 12
	s_cselect_b32 s41, s46, s15
	s_cselect_b32 s40, s47, s14
	s_cselect_b32 s15, s48, s55
	s_cselect_b32 s14, s49, s53
	s_add_i32 s23, 0, 0x14000
	v_add_u32_e32 v154, s22, v191
	v_add_u32_e32 v162, s23, v191
	ds_read_b128 v[130:133], v154
	ds_read_b128 v[146:149], v154 offset:1024
	ds_read_b128 v[150:153], v154 offset:2048
	ds_read_b128 v[154:157], v154 offset:3072
	ds_read_b128 v[158:161], v162
	ds_read_b128 v[178:181], v162 offset:1024
	ds_read_b128 v[182:185], v162 offset:2048
	ds_read_b128 v[186:189], v162 offset:3072
	v_lshl_add_u64 v[162:163], s[12:13], 0, v[142:143]
	s_add_i32 m0, s30, 0xc000
	ds_read_b128 v[204:207], v203
	ds_read_b128 v[208:211], v203 offset:1024
	ds_read_b128 v[212:215], v203 offset:2048
	ds_read_b128 v[216:219], v203 offset:3072
	ds_read_b128 v[220:223], v203 offset:4096
	ds_read_b128 v[224:227], v203 offset:5120
	ds_read_b128 v[228:231], v203 offset:6144
	ds_read_b128 v[232:235], v203 offset:7168
	global_load_lds_dwordx4 v[162:163], off
	v_lshl_add_u64 v[162:163], s[12:13], 0, v[144:145]
	s_add_i32 m0, s30, 0xe000
	s_nop 0
	global_load_lds_dwordx4 v[162:163], off
	s_waitcnt vmcnt(8)
	s_waitcnt lgkmcnt(0)
	s_barrier
	s_setprio 1
	s_waitcnt lgkmcnt(0)
	v_mfma_f32_16x16x32_bf16 v[126:129], v[130:133], v[204:207], 0
	v_mfma_f32_16x16x32_bf16 v[122:125], v[150:153], v[204:207], 0
	v_mfma_f32_16x16x32_bf16 v[110:113], v[130:133], v[212:215], 0
	v_mfma_f32_16x16x32_bf16 v[106:109], v[150:153], v[212:215], 0
	v_mfma_f32_16x16x32_bf16 v[94:97], v[130:133], v[220:223], 0
	v_mfma_f32_16x16x32_bf16 v[90:93], v[150:153], v[220:223], 0
	v_mfma_f32_16x16x32_bf16 v[78:81], v[130:133], v[228:231], 0
	v_mfma_f32_16x16x32_bf16 v[74:77], v[150:153], v[228:231], 0
	v_mfma_f32_16x16x32_bf16 v[118:121], v[158:161], v[204:207], 0
	v_mfma_f32_16x16x32_bf16 v[114:117], v[182:185], v[204:207], 0
	v_mfma_f32_16x16x32_bf16 v[102:105], v[158:161], v[212:215], 0
	v_mfma_f32_16x16x32_bf16 v[98:101], v[182:185], v[212:215], 0
	v_mfma_f32_16x16x32_bf16 v[86:89], v[158:161], v[220:223], 0
	v_mfma_f32_16x16x32_bf16 v[82:85], v[182:185], v[220:223], 0
	v_mfma_f32_16x16x32_bf16 v[70:73], v[158:161], v[228:231], 0
	v_mfma_f32_16x16x32_bf16 v[66:69], v[182:185], v[228:231], 0
	v_mfma_f32_16x16x32_bf16 v[126:129], v[146:149], v[208:211], v[126:129]
	v_mfma_f32_16x16x32_bf16 v[122:125], v[154:157], v[208:211], v[122:125]
	v_mfma_f32_16x16x32_bf16 v[110:113], v[146:149], v[216:219], v[110:113]
	v_mfma_f32_16x16x32_bf16 v[106:109], v[154:157], v[216:219], v[106:109]
	v_mfma_f32_16x16x32_bf16 v[94:97], v[146:149], v[224:227], v[94:97]
	v_mfma_f32_16x16x32_bf16 v[90:93], v[154:157], v[224:227], v[90:93]
	v_mfma_f32_16x16x32_bf16 v[78:81], v[146:149], v[232:235], v[78:81]
	v_mfma_f32_16x16x32_bf16 v[74:77], v[154:157], v[232:235], v[74:77]
	v_mfma_f32_16x16x32_bf16 v[118:121], v[178:181], v[208:211], v[118:121]
	v_mfma_f32_16x16x32_bf16 v[114:117], v[186:189], v[208:211], v[114:117]
	v_mfma_f32_16x16x32_bf16 v[102:105], v[178:181], v[216:219], v[102:105]
	v_mfma_f32_16x16x32_bf16 v[98:101], v[186:189], v[216:219], v[98:101]
	v_mfma_f32_16x16x32_bf16 v[86:89], v[178:181], v[224:227], v[86:89]
	v_mfma_f32_16x16x32_bf16 v[82:85], v[186:189], v[224:227], v[82:85]
	v_mfma_f32_16x16x32_bf16 v[70:73], v[178:181], v[232:235], v[70:73]
	v_mfma_f32_16x16x32_bf16 v[66:69], v[186:189], v[232:235], v[66:69]
	s_setprio 0
	s_barrier
	s_add_i32 s22, s22, s29
	v_lshl_add_u64 v[162:163], s[14:15], 0, v[0:1]
	s_mov_b32 m0, s22
	ds_read_b128 v[204:207], v203 offset:16384
	ds_read_b128 v[208:211], v203 offset:17408
	ds_read_b128 v[212:215], v203 offset:18432
	ds_read_b128 v[216:219], v203 offset:19456
	ds_read_b128 v[220:223], v203 offset:20480
	ds_read_b128 v[224:227], v203 offset:21504
	ds_read_b128 v[228:231], v203 offset:22528
	ds_read_b128 v[232:235], v203 offset:23552
	global_load_lds_dwordx4 v[162:163], off
	s_add_i32 m0, s22, 0x2000
	s_add_u32 s66, s14, 0x40000
	v_lshl_add_u64 v[236:237], s[14:15], 0, v[134:135]
	s_addc_u32 s67, s15, 0
	s_add_i32 s22, s23, s29
	global_load_lds_dwordx4 v[236:237], off
	v_lshl_add_u64 v[238:239], s[66:67], 0, v[0:1]
	s_mov_b32 m0, s22
	v_lshl_add_u64 v[240:241], s[40:41], 0, v[136:137]
	global_load_lds_dwordx4 v[238:239], off
	v_lshl_add_u64 v[238:239], s[66:67], 0, v[134:135]
	s_add_i32 m0, s22, 0x2000
	s_nop 0
	global_load_lds_dwordx4 v[238:239], off
	v_lshl_add_u64 v[238:239], s[40:41], 0, v[138:139]
	s_mov_b32 m0, s30
	s_nop 0
	global_load_lds_dwordx4 v[238:239], off
	s_mov_b32 m0, s31
	s_nop 0
	global_load_lds_dwordx4 v[240:241], off
	s_waitcnt vmcnt(8)
	s_waitcnt lgkmcnt(0)
	s_barrier
; #define PG8_STAGE(bufoff, gbase, voff) do { _Pragma("unroll") for (int _i = 0; _i < 2; ++_i) \
;         __builtin_amdgcn_global_load_lds((const unsigned*)((const char*)(gbase) + (voff)[_i]), (PG8_LAS unsigned*)(lds + (bufoff) + ldsw + _i * 8192), 16, 0, 0); } while (0)
; #define PG8_LDA(dst, b, h) do { _Pragma("unroll") for (int m = 0; m < 4; ++m) _Pragma("unroll") for (int k = 0; k < 2; ++k) dst[m][k] = *(const PG8_LAS bf16x8*)(lds + PG8_SA(b, h) + aoff + m * 2048 + k * 1024); } while (0)
; #define PG8_LDB(dst, b, h) do { _Pragma("unroll") for (int n = 0; n < 2; ++n) _Pragma("unroll") for (int k = 0; k < 2; ++k) dst[n][k] = *(const PG8_LAS bf16x8*)(lds + PG8_SB(b, h) + boff + n * 2048 + k * 1024); } while (0)
; #define PG8_MMA_NP(ai, bj, At, Bt) do { _Pragma("unroll") for (int m = 0; m < 4; ++m) _Pragma("unroll") for (int n = 0; n < 2; ++n) _Pragma("unroll") for (int k = 0; k < 2; ++k) \
;         acc[ai][bj][m][n] = __builtin_amdgcn_mfma_f32_16x16x32_bf16(Bt[n][k], At[m][k], acc[ai][bj][m][n], 0, 0, 0); } while (0)
; #define PG8_WAIT_V(n) asm volatile("s_waitcnt vmcnt(" #n ")" ::: "memory")
; #define PG8_WAIT_L(n) asm volatile("s_waitcnt lgkmcnt(" #n ")" ::: "memory")
; #define PG8_BAR __builtin_amdgcn_s_barrier()
; #define PG8_SCHED __builtin_amdgcn_sched_barrier(0)
; template <class Epi, class Sched, bool ALIGN_EPI = false, bool SP2 = false>
; __device__ __forceinline__ void gemm_phase(PG8_LAS unsigned char* lds, const Gemm g, const Sched& S, const Epi& E) {
;     ...
;             PG8_WAIT_V(8); PG8_WAIT_L(0); PG8_BAR; __builtin_amdgcn_s_setprio(1); PG8_MMA_NP(1, 0, At, B0); PG8_MMA_NP(1, 1, At, B1); __builtin_amdgcn_s_setprio(0); PG8_BAR; PG8_SCHED;
;             PG8_LDB(B0, 1, 0); PG8_LDB(B1, 1, 1); PG8_SCHED; PG8_LDA(At, 1, 0); PG8_STAGE(PG8_SA(0, 1), a2 + hstep, voffA);
;             PG8_WAIT_V(8); PG8_WAIT_L(0); PG8_BAR; __builtin_amdgcn_s_setprio(1); PG8_MMA_NP(0, 0, At, B0); PG8_MMA_NP(0, 1, At, B1); __builtin_amdgcn_s_setprio(0); PG8_BAR; PG8_SCHED;
;             PG8_LDA(At, 1, 1); PG8_STAGE(PG8_SB(1, 0), b3, voffB); PG8_STAGE(PG8_SB(1, 1), b3 + hstep, voffB); PG8_STAGE(PG8_SA(1, 0), a3, voffA);
	s_setprio 1
	s_waitcnt lgkmcnt(0)
	v_mfma_f32_16x16x32_bf16 v[62:65], v[130:133], v[204:207], 0
	v_mfma_f32_16x16x32_bf16 v[58:61], v[150:153], v[204:207], 0
	v_mfma_f32_16x16x32_bf16 v[46:49], v[130:133], v[212:215], 0
	v_mfma_f32_16x16x32_bf16 v[42:45], v[150:153], v[212:215], 0
	v_mfma_f32_16x16x32_bf16 v[30:33], v[130:133], v[220:223], 0
	v_mfma_f32_16x16x32_bf16 v[26:29], v[150:153], v[220:223], 0
	v_mfma_f32_16x16x32_bf16 v[14:17], v[130:133], v[228:231], 0
	v_mfma_f32_16x16x32_bf16 v[10:13], v[150:153], v[228:231], 0
	v_mfma_f32_16x16x32_bf16 v[54:57], v[158:161], v[204:207], 0
	v_mfma_f32_16x16x32_bf16 v[50:53], v[182:185], v[204:207], 0
	v_mfma_f32_16x16x32_bf16 v[38:41], v[158:161], v[212:215], 0
	v_mfma_f32_16x16x32_bf16 v[34:37], v[182:185], v[212:215], 0
	v_mfma_f32_16x16x32_bf16 v[22:25], v[158:161], v[220:223], 0
	v_mfma_f32_16x16x32_bf16 v[18:21], v[182:185], v[220:223], 0
	v_mfma_f32_16x16x32_bf16 v[6:9], v[158:161], v[228:231], 0
	v_mfma_f32_16x16x32_bf16 v[2:5], v[182:185], v[228:231], 0
	v_mfma_f32_16x16x32_bf16 v[62:65], v[146:149], v[208:211], v[62:65]
	v_mfma_f32_16x16x32_bf16 v[58:61], v[154:157], v[208:211], v[58:61]
	v_mfma_f32_16x16x32_bf16 v[46:49], v[146:149], v[216:219], v[46:49]
	v_mfma_f32_16x16x32_bf16 v[42:45], v[154:157], v[216:219], v[42:45]
	v_mfma_f32_16x16x32_bf16 v[30:33], v[146:149], v[224:227], v[30:33]
	v_mfma_f32_16x16x32_bf16 v[26:29], v[154:157], v[224:227], v[26:29]
	v_mfma_f32_16x16x32_bf16 v[14:17], v[146:149], v[232:235], v[14:17]
	v_mfma_f32_16x16x32_bf16 v[10:13], v[154:157], v[232:235], v[10:13]
	v_mfma_f32_16x16x32_bf16 v[54:57], v[178:181], v[208:211], v[54:57]
	v_mfma_f32_16x16x32_bf16 v[50:53], v[186:189], v[208:211], v[50:53]
	v_mfma_f32_16x16x32_bf16 v[38:41], v[178:181], v[216:219], v[38:41]
	v_mfma_f32_16x16x32_bf16 v[34:37], v[186:189], v[216:219], v[34:37]
	v_mfma_f32_16x16x32_bf16 v[22:25], v[178:181], v[224:227], v[22:25]
	v_mfma_f32_16x16x32_bf16 v[18:21], v[186:189], v[224:227], v[18:21]
	v_mfma_f32_16x16x32_bf16 v[6:9], v[178:181], v[232:235], v[6:9]
	v_mfma_f32_16x16x32_bf16 v[2:5], v[186:189], v[232:235], v[2:5]
	s_setprio 0
	s_barrier
	s_add_i32 s22, 0, 0x18000
	s_add_i32 s23, 0, 0x1c000
	v_add_u32_e32 v154, s22, v191
	v_add_u32_e32 v186, s23, v191
	ds_read_b128 v[130:133], v154
	ds_read_b128 v[146:149], v154 offset:1024
	ds_read_b128 v[150:153], v154 offset:2048
	ds_read_b128 v[154:157], v154 offset:3072
	ds_read_b128 v[158:161], v186
	ds_read_b128 v[178:181], v186 offset:1024
	ds_read_b128 v[182:185], v186 offset:2048
	ds_read_b128 v[186:189], v186 offset:3072
	s_add_u32 s40, s40, 0x40000
	s_addc_u32 s41, s41, 0
	s_mov_b32 m0, s60
	v_lshl_add_u64 v[242:243], s[40:41], 0, v[138:139]
	ds_read_b128 v[204:207], v203 offset:32768
	ds_read_b128 v[208:211], v203 offset:33792
	ds_read_b128 v[212:215], v203 offset:34816
	ds_read_b128 v[216:219], v203 offset:35840
	ds_read_b128 v[220:223], v203 offset:36864
	ds_read_b128 v[224:227], v203 offset:37888
	ds_read_b128 v[228:231], v203 offset:38912
	ds_read_b128 v[232:235], v203 offset:39936
	global_load_lds_dwordx4 v[242:243], off
	v_lshl_add_u64 v[242:243], s[40:41], 0, v[136:137]
	s_mov_b32 m0, s61
	s_nop 0
	global_load_lds_dwordx4 v[242:243], off
	s_waitcnt vmcnt(8)
	s_waitcnt lgkmcnt(0)
	s_barrier
	s_setprio 1
	s_waitcnt lgkmcnt(0)
	v_mfma_f32_16x16x32_bf16 v[126:129], v[130:133], v[204:207], v[126:129]
	v_mfma_f32_16x16x32_bf16 v[122:125], v[150:153], v[204:207], v[122:125]
	v_mfma_f32_16x16x32_bf16 v[110:113], v[130:133], v[212:215], v[110:113]
	v_mfma_f32_16x16x32_bf16 v[106:109], v[150:153], v[212:215], v[106:109]
	v_mfma_f32_16x16x32_bf16 v[94:97], v[130:133], v[220:223], v[94:97]
	v_mfma_f32_16x16x32_bf16 v[90:93], v[150:153], v[220:223], v[90:93]
	v_mfma_f32_16x16x32_bf16 v[78:81], v[130:133], v[228:231], v[78:81]
	v_mfma_f32_16x16x32_bf16 v[74:77], v[150:153], v[228:231], v[74:77]
	v_mfma_f32_16x16x32_bf16 v[118:121], v[158:161], v[204:207], v[118:121]
	v_mfma_f32_16x16x32_bf16 v[114:117], v[182:185], v[204:207], v[114:117]
	v_mfma_f32_16x16x32_bf16 v[102:105], v[158:161], v[212:215], v[102:105]
	v_mfma_f32_16x16x32_bf16 v[98:101], v[182:185], v[212:215], v[98:101]
	v_mfma_f32_16x16x32_bf16 v[86:89], v[158:161], v[220:223], v[86:89]
	v_mfma_f32_16x16x32_bf16 v[82:85], v[182:185], v[220:223], v[82:85]
	v_mfma_f32_16x16x32_bf16 v[70:73], v[158:161], v[228:231], v[70:73]
	v_mfma_f32_16x16x32_bf16 v[66:69], v[182:185], v[228:231], v[66:69]
	v_mfma_f32_16x16x32_bf16 v[126:129], v[146:149], v[208:211], v[126:129]
	v_mfma_f32_16x16x32_bf16 v[122:125], v[154:157], v[208:211], v[122:125]
	v_mfma_f32_16x16x32_bf16 v[110:113], v[146:149], v[216:219], v[110:113]
	v_mfma_f32_16x16x32_bf16 v[106:109], v[154:157], v[216:219], v[106:109]
	v_mfma_f32_16x16x32_bf16 v[94:97], v[146:149], v[224:227], v[94:97]
	v_mfma_f32_16x16x32_bf16 v[90:93], v[154:157], v[224:227], v[90:93]
	v_mfma_f32_16x16x32_bf16 v[78:81], v[146:149], v[232:235], v[78:81]
	v_mfma_f32_16x16x32_bf16 v[74:77], v[154:157], v[232:235], v[74:77]
	v_mfma_f32_16x16x32_bf16 v[118:121], v[178:181], v[208:211], v[118:121]
	v_mfma_f32_16x16x32_bf16 v[114:117], v[186:189], v[208:211], v[114:117]
	v_mfma_f32_16x16x32_bf16 v[102:105], v[178:181], v[216:219], v[102:105]
	v_mfma_f32_16x16x32_bf16 v[98:101], v[186:189], v[216:219], v[98:101]
	v_mfma_f32_16x16x32_bf16 v[86:89], v[178:181], v[224:227], v[86:89]
	v_mfma_f32_16x16x32_bf16 v[82:85], v[186:189], v[224:227], v[82:85]
	v_mfma_f32_16x16x32_bf16 v[70:73], v[178:181], v[232:235], v[70:73]
	v_mfma_f32_16x16x32_bf16 v[66:69], v[186:189], v[232:235], v[66:69]
	s_setprio 0
	s_barrier
; #define PG8_STAGE(bufoff, gbase, voff) do { _Pragma("unroll") for (int _i = 0; _i < 2; ++_i) \
;         __builtin_amdgcn_global_load_lds((const unsigned*)((const char*)(gbase) + (voff)[_i]), (PG8_LAS unsigned*)(lds + (bufoff) + ldsw + _i * 8192), 16, 0, 0); } while (0)
; #define PG8_LDA(dst, b, h) do { _Pragma("unroll") for (int m = 0; m < 4; ++m) _Pragma("unroll") for (int k = 0; k < 2; ++k) dst[m][k] = *(const PG8_LAS bf16x8*)(lds + PG8_SA(b, h) + aoff + m * 2048 + k * 1024); } while (0)
; #define PG8_MMA_NP(ai, bj, At, Bt) do { _Pragma("unroll") for (int m = 0; m < 4; ++m) _Pragma("unroll") for (int n = 0; n < 2; ++n) _Pragma("unroll") for (int k = 0; k < 2; ++k) \
;         acc[ai][bj][m][n] = __builtin_amdgcn_mfma_f32_16x16x32_bf16(Bt[n][k], At[m][k], acc[ai][bj][m][n], 0, 0, 0); } while (0)
; #define PG8_WAIT_V(n) asm volatile("s_waitcnt vmcnt(" #n ")" ::: "memory")
; #define PG8_WAIT_L(n) asm volatile("s_waitcnt lgkmcnt(" #n ")" ::: "memory")
; #define PG8_BAR __builtin_amdgcn_s_barrier()
; #define PG8_SCHED __builtin_amdgcn_sched_barrier(0)
; template <class Epi, class Sched, bool ALIGN_EPI = false, bool SP2 = false>
; __device__ __forceinline__ void gemm_phase(PG8_LAS unsigned char* lds, const Gemm g, const Sched& S, const Epi& E) {
;     ...
;             PG8_LDA(At, 1, 1); PG8_STAGE(PG8_SB(1, 0), b3, voffB); PG8_STAGE(PG8_SB(1, 1), b3 + hstep, voffB); PG8_STAGE(PG8_SA(1, 0), a3, voffA);
;             PG8_WAIT_V(8); PG8_WAIT_L(0); PG8_BAR; __builtin_amdgcn_s_setprio(1); PG8_MMA_NP(1, 0, At, B0); PG8_MMA_NP(1, 1, At, B1); __builtin_amdgcn_s_setprio(0); PG8_BAR; PG8_SCHED;
	s_add_i32 s22, s22, s29
	v_lshl_add_u64 v[162:163], v[162:163], 0, s[20:21]
	s_mov_b32 m0, s22
	ds_read_b128 v[204:207], v203 offset:49152
	ds_read_b128 v[208:211], v203 offset:50176
	ds_read_b128 v[212:215], v203 offset:51200
	ds_read_b128 v[216:219], v203 offset:52224
	ds_read_b128 v[220:223], v203 offset:53248
	ds_read_b128 v[224:227], v203 offset:54272
	ds_read_b128 v[228:231], v203 offset:55296
	ds_read_b128 v[232:235], v203 offset:56320
	global_load_lds_dwordx4 v[162:163], off
	s_add_i32 m0, s22, 0x2000
	s_add_u32 s14, s14, 0x40080
	v_lshl_add_u64 v[162:163], v[236:237], 0, s[20:21]
	s_addc_u32 s15, s15, 0
	s_add_i32 s22, s23, s29
	global_load_lds_dwordx4 v[162:163], off
	v_lshl_add_u64 v[162:163], s[14:15], 0, v[0:1]
	s_mov_b32 m0, s22
	s_nop 0
	global_load_lds_dwordx4 v[162:163], off
	v_lshl_add_u64 v[162:163], s[14:15], 0, v[134:135]
	s_add_i32 m0, s22, 0x2000
	s_nop 0
	global_load_lds_dwordx4 v[162:163], off
	v_lshl_add_u64 v[162:163], v[238:239], 0, s[20:21]
	s_mov_b32 m0, s62
	s_nop 0
	global_load_lds_dwordx4 v[162:163], off
	v_lshl_add_u64 v[162:163], v[240:241], 0, s[20:21]
	s_mov_b32 m0, s63
	s_nop 0
	global_load_lds_dwordx4 v[162:163], off
	s_waitcnt vmcnt(8)
	s_waitcnt lgkmcnt(0)
	s_barrier
	s_setprio 1
	s_waitcnt lgkmcnt(0)
	v_mfma_f32_16x16x32_bf16 v[62:65], v[130:133], v[204:207], v[62:65]
	v_mfma_f32_16x16x32_bf16 v[58:61], v[150:153], v[204:207], v[58:61]
	v_mfma_f32_16x16x32_bf16 v[46:49], v[130:133], v[212:215], v[46:49]
	v_mfma_f32_16x16x32_bf16 v[42:45], v[150:153], v[212:215], v[42:45]
	v_mfma_f32_16x16x32_bf16 v[30:33], v[130:133], v[220:223], v[30:33]
	v_mfma_f32_16x16x32_bf16 v[26:29], v[150:153], v[220:223], v[26:29]
	v_mfma_f32_16x16x32_bf16 v[14:17], v[130:133], v[228:231], v[14:17]
	v_mfma_f32_16x16x32_bf16 v[10:13], v[150:153], v[228:231], v[10:13]
	v_mfma_f32_16x16x32_bf16 v[54:57], v[158:161], v[204:207], v[54:57]
	v_mfma_f32_16x16x32_bf16 v[50:53], v[182:185], v[204:207], v[50:53]
	v_mfma_f32_16x16x32_bf16 v[38:41], v[158:161], v[212:215], v[38:41]
	v_mfma_f32_16x16x32_bf16 v[34:37], v[182:185], v[212:215], v[34:37]
	v_mfma_f32_16x16x32_bf16 v[22:25], v[158:161], v[220:223], v[22:25]
	v_mfma_f32_16x16x32_bf16 v[18:21], v[182:185], v[220:223], v[18:21]
	v_mfma_f32_16x16x32_bf16 v[6:9], v[158:161], v[228:231], v[6:9]
	v_mfma_f32_16x16x32_bf16 v[2:5], v[182:185], v[228:231], v[2:5]
	v_mfma_f32_16x16x32_bf16 v[62:65], v[146:149], v[208:211], v[62:65]
	v_mfma_f32_16x16x32_bf16 v[58:61], v[154:157], v[208:211], v[58:61]
	v_mfma_f32_16x16x32_bf16 v[46:49], v[146:149], v[216:219], v[46:49]
	v_mfma_f32_16x16x32_bf16 v[42:45], v[154:157], v[216:219], v[42:45]
	v_mfma_f32_16x16x32_bf16 v[30:33], v[146:149], v[224:227], v[30:33]
	v_mfma_f32_16x16x32_bf16 v[26:29], v[154:157], v[224:227], v[26:29]
	v_mfma_f32_16x16x32_bf16 v[14:17], v[146:149], v[232:235], v[14:17]
	v_mfma_f32_16x16x32_bf16 v[10:13], v[154:157], v[232:235], v[10:13]
	v_mfma_f32_16x16x32_bf16 v[54:57], v[178:181], v[208:211], v[54:57]
	v_mfma_f32_16x16x32_bf16 v[50:53], v[186:189], v[208:211], v[50:53]
	v_mfma_f32_16x16x32_bf16 v[38:41], v[178:181], v[216:219], v[38:41]
	v_mfma_f32_16x16x32_bf16 v[34:37], v[186:189], v[216:219], v[34:37]
	v_mfma_f32_16x16x32_bf16 v[22:25], v[178:181], v[224:227], v[22:25]
	v_mfma_f32_16x16x32_bf16 v[18:21], v[186:189], v[224:227], v[18:21]
	v_mfma_f32_16x16x32_bf16 v[6:9], v[178:181], v[232:235], v[6:9]
	v_mfma_f32_16x16x32_bf16 v[2:5], v[186:189], v[232:235], v[2:5]
	s_setprio 0
	s_barrier
	s_add_i32 s65, s65, 2
	s_add_u32 s12, s12, 0x100
	s_addc_u32 s13, s13, 0
	s_add_u32 s53, s53, 0x100
	s_addc_u32 s55, s55, 0
	s_cmp_gt_u32 s65, 13
	s_cbranch_scc0 .LBB0_370
	s_branch .Lkexit_2
	.p2align 3

; #define PG8_STAGE(bufoff, gbase, voff) do { _Pragma("unroll") for (int _i = 0; _i < 2; ++_i) \
;         __builtin_amdgcn_global_load_lds((const unsigned*)((const char*)(gbase) + (voff)[_i]), (PG8_LAS unsigned*)(lds + (bufoff) + ldsw + _i * 8192), 16, 0, 0); } while (0)
; #define PG8_LDA(dst, b, h) do { _Pragma("unroll") for (int m = 0; m < 4; ++m) _Pragma("unroll") for (int k = 0; k < 2; ++k) dst[m][k] = *(const PG8_LAS bf16x8*)(lds + PG8_SA(b, h) + aoff + m * 2048 + k * 1024); } while (0)
; #define PG8_LDB(dst, b, h) do { _Pragma("unroll") for (int n = 0; n < 2; ++n) _Pragma("unroll") for (int k = 0; k < 2; ++k) dst[n][k] = *(const PG8_LAS bf16x8*)(lds + PG8_SB(b, h) + boff + n * 2048 + k * 1024); } while (0)
; #define PG8_MMA_NP(ai, bj, At, Bt) do { _Pragma("unroll") for (int m = 0; m < 4; ++m) _Pragma("unroll") for (int n = 0; n < 2; ++n) _Pragma("unroll") for (int k = 0; k < 2; ++k) \
;         acc[ai][bj][m][n] = __builtin_amdgcn_mfma_f32_16x16x32_bf16(Bt[n][k], At[m][k], acc[ai][bj][m][n], 0, 0, 0); } while (0)
; #define PG8_WAIT_V(n) asm volatile("s_waitcnt vmcnt(" #n ")" ::: "memory")
; #define PG8_WAIT_L(n) asm volatile("s_waitcnt lgkmcnt(" #n ")" ::: "memory")
; #define PG8_BAR __builtin_amdgcn_s_barrier()
; #define PG8_SCHED __builtin_amdgcn_sched_barrier(0)
; template <class Epi, class Sched, bool ALIGN_EPI = false, bool SP2 = false>
; __device__ __forceinline__ void gemm_phase(PG8_LAS unsigned char* lds, const Gemm g, const Sched& S, const Epi& E) {
;     ...
;             PG8_LDB(B0, 0, 0); PG8_LDB(B1, 0, 1); PG8_SCHED; PG8_LDA(At, 0, 0); PG8_STAGE(PG8_SA(1, 1), a1 + hstep, voffA);
;             PG8_WAIT_V(8); PG8_WAIT_L(0); PG8_BAR; __builtin_amdgcn_s_setprio(1); PG8_MMA_NP(0, 0, At, B0); PG8_MMA_NP(0, 1, At, B1); __builtin_amdgcn_s_setprio(0); PG8_BAR; PG8_SCHED;
;             PG8_LDA(At, 0, 1); PG8_STAGE(PG8_SB(0, 0), b2, voffB); PG8_STAGE(PG8_SB(0, 1), b2 + hstep, voffB); PG8_STAGE(PG8_SA(0, 0), a2, voffA);
;             PG8_WAIT_V(8); PG8_WAIT_L(0); PG8_BAR; __builtin_amdgcn_s_setprio(1); PG8_MMA_NP(1, 0, At, B0); PG8_MMA_NP(1, 1, At, B1); __builtin_amdgcn_s_setprio(0); PG8_BAR; PG8_SCHED;
.LBB0_431:
	s_ashr_i32 s49, s48, 31
	s_lshl_b64 s[14:15], s[48:49], 19
	s_add_u32 s50, s10, s14
	s_addc_u32 s51, s29, s15
	s_and_b64 s[14:15], s[42:43], exec
	s_cselect_b32 s49, s51, s3
	s_cselect_b32 s59, s50, s2
	s_ashr_i32 s47, s46, 31
	s_lshl_b64 s[14:15], s[46:47], 19
	s_add_u32 s52, s86, s14
	s_addc_u32 s53, s87, s15
	s_and_b64 s[14:15], s[42:43], exec
	s_cselect_b32 s47, s53, s13
	s_cselect_b32 s60, s52, s12
	s_add_u32 s2, s2, 0x40080
	s_addc_u32 s3, s3, 0
	s_add_u32 s61, s12, 0x100
	s_addc_u32 s62, s13, 0
	s_mov_b32 s63, -2
	s_add_u32 s12, s2, 0xfffc0080
	s_addc_u32 s13, s3, -1
	s_add_i32 s22, 0, 0x10000
	s_cmp_eq_u32 s63, 12
	s_cselect_b32 s15, s49, s13
	s_cselect_b32 s14, s59, s12
	s_cselect_b32 s13, s47, s62
	s_cselect_b32 s12, s60, s61
	s_add_i32 s23, 0, 0x14000
	v_add_u32_e32 v154, s22, v159
	v_add_u32_e32 v162, s23, v159
	ds_read_b128 v[142:145], v154
	ds_read_b128 v[146:149], v154 offset:1024
	ds_read_b128 v[150:153], v154 offset:2048
	ds_read_b128 v[154:157], v154 offset:3072
	ds_read_b128 v[178:181], v162
	ds_read_b128 v[182:185], v162 offset:1024
	ds_read_b128 v[186:189], v162 offset:2048
	ds_read_b128 v[202:205], v162 offset:3072
	v_lshl_add_u64 v[162:163], s[2:3], 0, v[138:139]
	s_add_i32 m0, s30, 0xc000
	ds_read_b128 v[206:209], v161
	ds_read_b128 v[210:213], v161 offset:1024
	ds_read_b128 v[214:217], v161 offset:2048
	ds_read_b128 v[218:221], v161 offset:3072
	ds_read_b128 v[222:225], v161 offset:4096
	ds_read_b128 v[226:229], v161 offset:5120
	ds_read_b128 v[230:233], v161 offset:6144
	ds_read_b128 v[234:237], v161 offset:7168
	global_load_lds_dwordx4 v[162:163], off
	v_lshl_add_u64 v[162:163], s[2:3], 0, v[140:141]
	s_add_i32 m0, s30, 0xe000
	s_nop 0
	global_load_lds_dwordx4 v[162:163], off
	s_waitcnt vmcnt(8)
	s_waitcnt lgkmcnt(0)
	s_barrier
	s_setprio 1
	s_waitcnt lgkmcnt(0)
	v_mfma_f32_16x16x32_bf16 v[126:129], v[142:145], v[206:209], 0
	v_mfma_f32_16x16x32_bf16 v[122:125], v[150:153], v[206:209], 0
	v_mfma_f32_16x16x32_bf16 v[118:121], v[142:145], v[214:217], 0
	v_mfma_f32_16x16x32_bf16 v[114:117], v[150:153], v[214:217], 0
	v_mfma_f32_16x16x32_bf16 v[110:113], v[142:145], v[222:225], 0
	v_mfma_f32_16x16x32_bf16 v[106:109], v[150:153], v[222:225], 0
	v_mfma_f32_16x16x32_bf16 v[102:105], v[142:145], v[230:233], 0
	v_mfma_f32_16x16x32_bf16 v[98:101], v[150:153], v[230:233], 0
	v_mfma_f32_16x16x32_bf16 v[62:65], v[178:181], v[206:209], 0
	v_mfma_f32_16x16x32_bf16 v[58:61], v[186:189], v[206:209], 0
	v_mfma_f32_16x16x32_bf16 v[54:57], v[178:181], v[214:217], 0
	v_mfma_f32_16x16x32_bf16 v[50:53], v[186:189], v[214:217], 0
	v_mfma_f32_16x16x32_bf16 v[46:49], v[178:181], v[222:225], 0
	v_mfma_f32_16x16x32_bf16 v[42:45], v[186:189], v[222:225], 0
	v_mfma_f32_16x16x32_bf16 v[38:41], v[178:181], v[230:233], 0
	v_mfma_f32_16x16x32_bf16 v[34:37], v[186:189], v[230:233], 0
	v_mfma_f32_16x16x32_bf16 v[126:129], v[146:149], v[210:213], v[126:129]
	v_mfma_f32_16x16x32_bf16 v[122:125], v[154:157], v[210:213], v[122:125]
	v_mfma_f32_16x16x32_bf16 v[118:121], v[146:149], v[218:221], v[118:121]
	v_mfma_f32_16x16x32_bf16 v[114:117], v[154:157], v[218:221], v[114:117]
	v_mfma_f32_16x16x32_bf16 v[110:113], v[146:149], v[226:229], v[110:113]
	v_mfma_f32_16x16x32_bf16 v[106:109], v[154:157], v[226:229], v[106:109]
	v_mfma_f32_16x16x32_bf16 v[102:105], v[146:149], v[234:237], v[102:105]
	v_mfma_f32_16x16x32_bf16 v[98:101], v[154:157], v[234:237], v[98:101]
	v_mfma_f32_16x16x32_bf16 v[62:65], v[182:185], v[210:213], v[62:65]
	v_mfma_f32_16x16x32_bf16 v[58:61], v[202:205], v[210:213], v[58:61]
	v_mfma_f32_16x16x32_bf16 v[54:57], v[182:185], v[218:221], v[54:57]
	v_mfma_f32_16x16x32_bf16 v[50:53], v[202:205], v[218:221], v[50:53]
	v_mfma_f32_16x16x32_bf16 v[46:49], v[182:185], v[226:229], v[46:49]
	v_mfma_f32_16x16x32_bf16 v[42:45], v[202:205], v[226:229], v[42:45]
	v_mfma_f32_16x16x32_bf16 v[38:41], v[182:185], v[234:237], v[38:41]
	v_mfma_f32_16x16x32_bf16 v[34:37], v[202:205], v[234:237], v[34:37]
	s_setprio 0
	s_barrier
	s_add_i32 s22, s22, s8
	v_lshl_add_u64 v[162:163], s[12:13], 0, v[0:1]
	s_mov_b32 m0, s22
	ds_read_b128 v[206:209], v161 offset:16384
	ds_read_b128 v[210:213], v161 offset:17408
	ds_read_b128 v[214:217], v161 offset:18432
	ds_read_b128 v[218:221], v161 offset:19456
	ds_read_b128 v[222:225], v161 offset:20480
	ds_read_b128 v[226:229], v161 offset:21504
	ds_read_b128 v[230:233], v161 offset:22528
	ds_read_b128 v[234:237], v161 offset:23552
	global_load_lds_dwordx4 v[162:163], off
	s_add_i32 m0, s22, 0x2000
	s_add_u32 s64, s12, 0x40000
	v_lshl_add_u64 v[190:191], s[12:13], 0, v[130:131]
	s_addc_u32 s65, s13, 0
	s_add_i32 s22, s23, s8
	global_load_lds_dwordx4 v[190:191], off
	v_lshl_add_u64 v[238:239], s[64:65], 0, v[0:1]
	s_mov_b32 m0, s22
	v_lshl_add_u64 v[240:241], s[14:15], 0, v[132:133]
	global_load_lds_dwordx4 v[238:239], off
	v_lshl_add_u64 v[238:239], s[64:65], 0, v[130:131]
	s_add_i32 m0, s22, 0x2000
	s_nop 0
	global_load_lds_dwordx4 v[238:239], off
	v_lshl_add_u64 v[238:239], s[14:15], 0, v[134:135]
	s_mov_b32 m0, s30
	s_nop 0
	global_load_lds_dwordx4 v[238:239], off
	s_mov_b32 m0, s31
	s_nop 0
	global_load_lds_dwordx4 v[240:241], off
	s_waitcnt vmcnt(8)
	s_waitcnt lgkmcnt(0)
	s_barrier
; #define PG8_STAGE(bufoff, gbase, voff) do { _Pragma("unroll") for (int _i = 0; _i < 2; ++_i) \
;         __builtin_amdgcn_global_load_lds((const unsigned*)((const char*)(gbase) + (voff)[_i]), (PG8_LAS unsigned*)(lds + (bufoff) + ldsw + _i * 8192), 16, 0, 0); } while (0)
; #define PG8_LDA(dst, b, h) do { _Pragma("unroll") for (int m = 0; m < 4; ++m) _Pragma("unroll") for (int k = 0; k < 2; ++k) dst[m][k] = *(const PG8_LAS bf16x8*)(lds + PG8_SA(b, h) + aoff + m * 2048 + k * 1024); } while (0)
; #define PG8_LDB(dst, b, h) do { _Pragma("unroll") for (int n = 0; n < 2; ++n) _Pragma("unroll") for (int k = 0; k < 2; ++k) dst[n][k] = *(const PG8_LAS bf16x8*)(lds + PG8_SB(b, h) + boff + n * 2048 + k * 1024); } while (0)
; #define PG8_MMA_NP(ai, bj, At, Bt) do { _Pragma("unroll") for (int m = 0; m < 4; ++m) _Pragma("unroll") for (int n = 0; n < 2; ++n) _Pragma("unroll") for (int k = 0; k < 2; ++k) \
;         acc[ai][bj][m][n] = __builtin_amdgcn_mfma_f32_16x16x32_bf16(Bt[n][k], At[m][k], acc[ai][bj][m][n], 0, 0, 0); } while (0)
; #define PG8_WAIT_V(n) asm volatile("s_waitcnt vmcnt(" #n ")" ::: "memory")
; #define PG8_WAIT_L(n) asm volatile("s_waitcnt lgkmcnt(" #n ")" ::: "memory")
; #define PG8_BAR __builtin_amdgcn_s_barrier()
; #define PG8_SCHED __builtin_amdgcn_sched_barrier(0)
; template <class Epi, class Sched, bool ALIGN_EPI = false, bool SP2 = false>
; __device__ __forceinline__ void gemm_phase(PG8_LAS unsigned char* lds, const Gemm g, const Sched& S, const Epi& E) {
;     ...
;             PG8_WAIT_V(8); PG8_WAIT_L(0); PG8_BAR; __builtin_amdgcn_s_setprio(1); PG8_MMA_NP(1, 0, At, B0); PG8_MMA_NP(1, 1, At, B1); __builtin_amdgcn_s_setprio(0); PG8_BAR; PG8_SCHED;
;             PG8_LDB(B0, 1, 0); PG8_LDB(B1, 1, 1); PG8_SCHED; PG8_LDA(At, 1, 0); PG8_STAGE(PG8_SA(0, 1), a2 + hstep, voffA);
;             PG8_WAIT_V(8); PG8_WAIT_L(0); PG8_BAR; __builtin_amdgcn_s_setprio(1); PG8_MMA_NP(0, 0, At, B0); PG8_MMA_NP(0, 1, At, B1); __builtin_amdgcn_s_setprio(0); PG8_BAR; PG8_SCHED;
;             PG8_LDA(At, 1, 1); PG8_STAGE(PG8_SB(1, 0), b3, voffB); PG8_STAGE(PG8_SB(1, 1), b3 + hstep, voffB); PG8_STAGE(PG8_SA(1, 0), a3, voffA);
	s_setprio 1
	s_waitcnt lgkmcnt(0)
	v_mfma_f32_16x16x32_bf16 v[94:97], v[142:145], v[206:209], 0
	v_mfma_f32_16x16x32_bf16 v[90:93], v[150:153], v[206:209], 0
	v_mfma_f32_16x16x32_bf16 v[86:89], v[142:145], v[214:217], 0
	v_mfma_f32_16x16x32_bf16 v[82:85], v[150:153], v[214:217], 0
	v_mfma_f32_16x16x32_bf16 v[78:81], v[142:145], v[222:225], 0
	v_mfma_f32_16x16x32_bf16 v[74:77], v[150:153], v[222:225], 0
	v_mfma_f32_16x16x32_bf16 v[70:73], v[142:145], v[230:233], 0
	v_mfma_f32_16x16x32_bf16 v[66:69], v[150:153], v[230:233], 0
	v_mfma_f32_16x16x32_bf16 v[30:33], v[178:181], v[206:209], 0
	v_mfma_f32_16x16x32_bf16 v[26:29], v[186:189], v[206:209], 0
	v_mfma_f32_16x16x32_bf16 v[22:25], v[178:181], v[214:217], 0
	v_mfma_f32_16x16x32_bf16 v[18:21], v[186:189], v[214:217], 0
	v_mfma_f32_16x16x32_bf16 v[14:17], v[178:181], v[222:225], 0
	v_mfma_f32_16x16x32_bf16 v[10:13], v[186:189], v[222:225], 0
	v_mfma_f32_16x16x32_bf16 v[6:9], v[178:181], v[230:233], 0
	v_mfma_f32_16x16x32_bf16 v[2:5], v[186:189], v[230:233], 0
	v_mfma_f32_16x16x32_bf16 v[94:97], v[146:149], v[210:213], v[94:97]
	v_mfma_f32_16x16x32_bf16 v[90:93], v[154:157], v[210:213], v[90:93]
	v_mfma_f32_16x16x32_bf16 v[86:89], v[146:149], v[218:221], v[86:89]
	v_mfma_f32_16x16x32_bf16 v[82:85], v[154:157], v[218:221], v[82:85]
	v_mfma_f32_16x16x32_bf16 v[78:81], v[146:149], v[226:229], v[78:81]
	v_mfma_f32_16x16x32_bf16 v[74:77], v[154:157], v[226:229], v[74:77]
	v_mfma_f32_16x16x32_bf16 v[70:73], v[146:149], v[234:237], v[70:73]
	v_mfma_f32_16x16x32_bf16 v[66:69], v[154:157], v[234:237], v[66:69]
	v_mfma_f32_16x16x32_bf16 v[30:33], v[182:185], v[210:213], v[30:33]
	v_mfma_f32_16x16x32_bf16 v[26:29], v[202:205], v[210:213], v[26:29]
	v_mfma_f32_16x16x32_bf16 v[22:25], v[182:185], v[218:221], v[22:25]
	v_mfma_f32_16x16x32_bf16 v[18:21], v[202:205], v[218:221], v[18:21]
	v_mfma_f32_16x16x32_bf16 v[14:17], v[182:185], v[226:229], v[14:17]
	v_mfma_f32_16x16x32_bf16 v[10:13], v[202:205], v[226:229], v[10:13]
	v_mfma_f32_16x16x32_bf16 v[6:9], v[182:185], v[234:237], v[6:9]
	v_mfma_f32_16x16x32_bf16 v[2:5], v[202:205], v[234:237], v[2:5]
	s_setprio 0
	s_barrier
	s_add_i32 s22, 0, 0x18000
	s_add_i32 s23, 0, 0x1c000
	v_add_u32_e32 v154, s22, v159
	v_add_u32_e32 v202, s23, v159
	ds_read_b128 v[142:145], v154
	ds_read_b128 v[146:149], v154 offset:1024
	ds_read_b128 v[150:153], v154 offset:2048
	ds_read_b128 v[154:157], v154 offset:3072
	ds_read_b128 v[178:181], v202
	ds_read_b128 v[182:185], v202 offset:1024
	ds_read_b128 v[186:189], v202 offset:2048
	ds_read_b128 v[202:205], v202 offset:3072
	s_add_u32 s14, s14, 0x40000
	s_addc_u32 s15, s15, 0
	s_mov_b32 m0, s40
	v_lshl_add_u64 v[242:243], s[14:15], 0, v[134:135]
	ds_read_b128 v[206:209], v161 offset:32768
	ds_read_b128 v[210:213], v161 offset:33792
	ds_read_b128 v[214:217], v161 offset:34816
	ds_read_b128 v[218:221], v161 offset:35840
	ds_read_b128 v[222:225], v161 offset:36864
	ds_read_b128 v[226:229], v161 offset:37888
	ds_read_b128 v[230:233], v161 offset:38912
	ds_read_b128 v[234:237], v161 offset:39936
	global_load_lds_dwordx4 v[242:243], off
	v_lshl_add_u64 v[242:243], s[14:15], 0, v[132:133]
	s_mov_b32 m0, s41
	s_nop 0
	global_load_lds_dwordx4 v[242:243], off
	s_waitcnt vmcnt(8)
	s_waitcnt lgkmcnt(0)
	s_barrier
	s_setprio 1
	s_waitcnt lgkmcnt(0)
	v_mfma_f32_16x16x32_bf16 v[126:129], v[142:145], v[206:209], v[126:129]
	v_mfma_f32_16x16x32_bf16 v[122:125], v[150:153], v[206:209], v[122:125]
	v_mfma_f32_16x16x32_bf16 v[118:121], v[142:145], v[214:217], v[118:121]
	v_mfma_f32_16x16x32_bf16 v[114:117], v[150:153], v[214:217], v[114:117]
	v_mfma_f32_16x16x32_bf16 v[110:113], v[142:145], v[222:225], v[110:113]
	v_mfma_f32_16x16x32_bf16 v[106:109], v[150:153], v[222:225], v[106:109]
	v_mfma_f32_16x16x32_bf16 v[102:105], v[142:145], v[230:233], v[102:105]
	v_mfma_f32_16x16x32_bf16 v[98:101], v[150:153], v[230:233], v[98:101]
	v_mfma_f32_16x16x32_bf16 v[62:65], v[178:181], v[206:209], v[62:65]
	v_mfma_f32_16x16x32_bf16 v[58:61], v[186:189], v[206:209], v[58:61]
	v_mfma_f32_16x16x32_bf16 v[54:57], v[178:181], v[214:217], v[54:57]
	v_mfma_f32_16x16x32_bf16 v[50:53], v[186:189], v[214:217], v[50:53]
	v_mfma_f32_16x16x32_bf16 v[46:49], v[178:181], v[222:225], v[46:49]
	v_mfma_f32_16x16x32_bf16 v[42:45], v[186:189], v[222:225], v[42:45]
	v_mfma_f32_16x16x32_bf16 v[38:41], v[178:181], v[230:233], v[38:41]
	v_mfma_f32_16x16x32_bf16 v[34:37], v[186:189], v[230:233], v[34:37]
	v_mfma_f32_16x16x32_bf16 v[126:129], v[146:149], v[210:213], v[126:129]
	v_mfma_f32_16x16x32_bf16 v[122:125], v[154:157], v[210:213], v[122:125]
	v_mfma_f32_16x16x32_bf16 v[118:121], v[146:149], v[218:221], v[118:121]
	v_mfma_f32_16x16x32_bf16 v[114:117], v[154:157], v[218:221], v[114:117]
	v_mfma_f32_16x16x32_bf16 v[110:113], v[146:149], v[226:229], v[110:113]
	v_mfma_f32_16x16x32_bf16 v[106:109], v[154:157], v[226:229], v[106:109]
	v_mfma_f32_16x16x32_bf16 v[102:105], v[146:149], v[234:237], v[102:105]
	v_mfma_f32_16x16x32_bf16 v[98:101], v[154:157], v[234:237], v[98:101]
	v_mfma_f32_16x16x32_bf16 v[62:65], v[182:185], v[210:213], v[62:65]
	v_mfma_f32_16x16x32_bf16 v[58:61], v[202:205], v[210:213], v[58:61]
	v_mfma_f32_16x16x32_bf16 v[54:57], v[182:185], v[218:221], v[54:57]
	v_mfma_f32_16x16x32_bf16 v[50:53], v[202:205], v[218:221], v[50:53]
	v_mfma_f32_16x16x32_bf16 v[46:49], v[182:185], v[226:229], v[46:49]
	v_mfma_f32_16x16x32_bf16 v[42:45], v[202:205], v[226:229], v[42:45]
	v_mfma_f32_16x16x32_bf16 v[38:41], v[182:185], v[234:237], v[38:41]
	v_mfma_f32_16x16x32_bf16 v[34:37], v[202:205], v[234:237], v[34:37]
	s_setprio 0
	s_barrier
; #define PG8_STAGE(bufoff, gbase, voff) do { _Pragma("unroll") for (int _i = 0; _i < 2; ++_i) \
;         __builtin_amdgcn_global_load_lds((const unsigned*)((const char*)(gbase) + (voff)[_i]), (PG8_LAS unsigned*)(lds + (bufoff) + ldsw + _i * 8192), 16, 0, 0); } while (0)
; #define PG8_LDA(dst, b, h) do { _Pragma("unroll") for (int m = 0; m < 4; ++m) _Pragma("unroll") for (int k = 0; k < 2; ++k) dst[m][k] = *(const PG8_LAS bf16x8*)(lds + PG8_SA(b, h) + aoff + m * 2048 + k * 1024); } while (0)
; #define PG8_MMA_NP(ai, bj, At, Bt) do { _Pragma("unroll") for (int m = 0; m < 4; ++m) _Pragma("unroll") for (int n = 0; n < 2; ++n) _Pragma("unroll") for (int k = 0; k < 2; ++k) \
;         acc[ai][bj][m][n] = __builtin_amdgcn_mfma_f32_16x16x32_bf16(Bt[n][k], At[m][k], acc[ai][bj][m][n], 0, 0, 0); } while (0)
; #define PG8_WAIT_V(n) asm volatile("s_waitcnt vmcnt(" #n ")" ::: "memory")
; #define PG8_WAIT_L(n) asm volatile("s_waitcnt lgkmcnt(" #n ")" ::: "memory")
; #define PG8_BAR __builtin_amdgcn_s_barrier()
; #define PG8_SCHED __builtin_amdgcn_sched_barrier(0)
; template <class Epi, class Sched, bool ALIGN_EPI = false, bool SP2 = false>
; __device__ __forceinline__ void gemm_phase(PG8_LAS unsigned char* lds, const Gemm g, const Sched& S, const Epi& E) {
;     ...
;             PG8_LDA(At, 1, 1); PG8_STAGE(PG8_SB(1, 0), b3, voffB); PG8_STAGE(PG8_SB(1, 1), b3 + hstep, voffB); PG8_STAGE(PG8_SA(1, 0), a3, voffA);
;             PG8_WAIT_V(8); PG8_WAIT_L(0); PG8_BAR; __builtin_amdgcn_s_setprio(1); PG8_MMA_NP(1, 0, At, B0); PG8_MMA_NP(1, 1, At, B1); __builtin_amdgcn_s_setprio(0); PG8_BAR; PG8_SCHED;
	s_add_i32 s14, s22, s8
	v_lshl_add_u64 v[162:163], v[162:163], 0, s[20:21]
	s_mov_b32 m0, s14
	ds_read_b128 v[206:209], v161 offset:49152
	ds_read_b128 v[210:213], v161 offset:50176
	ds_read_b128 v[214:217], v161 offset:51200
	ds_read_b128 v[218:221], v161 offset:52224
	ds_read_b128 v[222:225], v161 offset:53248
	ds_read_b128 v[226:229], v161 offset:54272
	ds_read_b128 v[230:233], v161 offset:55296
	ds_read_b128 v[234:237], v161 offset:56320
	global_load_lds_dwordx4 v[162:163], off
	s_add_i32 m0, s14, 0x2000
	s_add_u32 s12, s12, 0x40080
	v_lshl_add_u64 v[162:163], v[190:191], 0, s[20:21]
	s_addc_u32 s13, s13, 0
	s_add_i32 s14, s23, s8
	global_load_lds_dwordx4 v[162:163], off
	v_lshl_add_u64 v[162:163], s[12:13], 0, v[0:1]
	s_mov_b32 m0, s14
	s_nop 0
	global_load_lds_dwordx4 v[162:163], off
	v_lshl_add_u64 v[162:163], s[12:13], 0, v[130:131]
	s_add_i32 m0, s14, 0x2000
	s_nop 0
	global_load_lds_dwordx4 v[162:163], off
	v_lshl_add_u64 v[162:163], v[238:239], 0, s[20:21]
	s_mov_b32 m0, s54
	s_nop 0
	global_load_lds_dwordx4 v[162:163], off
	v_lshl_add_u64 v[162:163], v[240:241], 0, s[20:21]
	s_mov_b32 m0, s55
	s_nop 0
	global_load_lds_dwordx4 v[162:163], off
	s_waitcnt vmcnt(8)
	s_waitcnt lgkmcnt(0)
	s_barrier
	s_setprio 1
	s_waitcnt lgkmcnt(0)
	v_mfma_f32_16x16x32_bf16 v[94:97], v[142:145], v[206:209], v[94:97]
	v_mfma_f32_16x16x32_bf16 v[90:93], v[150:153], v[206:209], v[90:93]
	v_mfma_f32_16x16x32_bf16 v[86:89], v[142:145], v[214:217], v[86:89]
	v_mfma_f32_16x16x32_bf16 v[82:85], v[150:153], v[214:217], v[82:85]
	v_mfma_f32_16x16x32_bf16 v[78:81], v[142:145], v[222:225], v[78:81]
	v_mfma_f32_16x16x32_bf16 v[74:77], v[150:153], v[222:225], v[74:77]
	v_mfma_f32_16x16x32_bf16 v[70:73], v[142:145], v[230:233], v[70:73]
	v_mfma_f32_16x16x32_bf16 v[66:69], v[150:153], v[230:233], v[66:69]
	v_mfma_f32_16x16x32_bf16 v[30:33], v[178:181], v[206:209], v[30:33]
	v_mfma_f32_16x16x32_bf16 v[26:29], v[186:189], v[206:209], v[26:29]
	v_mfma_f32_16x16x32_bf16 v[22:25], v[178:181], v[214:217], v[22:25]
	v_mfma_f32_16x16x32_bf16 v[18:21], v[186:189], v[214:217], v[18:21]
	v_mfma_f32_16x16x32_bf16 v[14:17], v[178:181], v[222:225], v[14:17]
	v_mfma_f32_16x16x32_bf16 v[10:13], v[186:189], v[222:225], v[10:13]
	v_mfma_f32_16x16x32_bf16 v[6:9], v[178:181], v[230:233], v[6:9]
	v_mfma_f32_16x16x32_bf16 v[2:5], v[186:189], v[230:233], v[2:5]
	v_mfma_f32_16x16x32_bf16 v[94:97], v[146:149], v[210:213], v[94:97]
	v_mfma_f32_16x16x32_bf16 v[90:93], v[154:157], v[210:213], v[90:93]
	v_mfma_f32_16x16x32_bf16 v[86:89], v[146:149], v[218:221], v[86:89]
	v_mfma_f32_16x16x32_bf16 v[82:85], v[154:157], v[218:221], v[82:85]
	v_mfma_f32_16x16x32_bf16 v[78:81], v[146:149], v[226:229], v[78:81]
	v_mfma_f32_16x16x32_bf16 v[74:77], v[154:157], v[226:229], v[74:77]
	v_mfma_f32_16x16x32_bf16 v[70:73], v[146:149], v[234:237], v[70:73]
	v_mfma_f32_16x16x32_bf16 v[66:69], v[154:157], v[234:237], v[66:69]
	v_mfma_f32_16x16x32_bf16 v[30:33], v[182:185], v[210:213], v[30:33]
	v_mfma_f32_16x16x32_bf16 v[26:29], v[202:205], v[210:213], v[26:29]
	v_mfma_f32_16x16x32_bf16 v[22:25], v[182:185], v[218:221], v[22:25]
	v_mfma_f32_16x16x32_bf16 v[18:21], v[202:205], v[218:221], v[18:21]
	v_mfma_f32_16x16x32_bf16 v[14:17], v[182:185], v[226:229], v[14:17]
	v_mfma_f32_16x16x32_bf16 v[10:13], v[202:205], v[226:229], v[10:13]
	v_mfma_f32_16x16x32_bf16 v[6:9], v[182:185], v[234:237], v[6:9]
	v_mfma_f32_16x16x32_bf16 v[2:5], v[202:205], v[234:237], v[2:5]
	s_setprio 0
	s_barrier
	s_add_i32 s63, s63, 2
	s_add_u32 s2, s2, 0x100
	s_addc_u32 s3, s3, 0
	s_add_u32 s61, s61, 0x100
	s_addc_u32 s62, s62, 0
	s_cmp_gt_u32 s63, 13
	s_cbranch_scc0 .LBB0_432
	s_branch .Lkexit_3
	.p2align 3

; #define PG8_STAGE(bufoff, gbase, voff) do { _Pragma("unroll") for (int _i = 0; _i < 2; ++_i) \
;         __builtin_amdgcn_global_load_lds((const unsigned*)((const char*)(gbase) + (voff)[_i]), (PG8_LAS unsigned*)(lds + (bufoff) + ldsw + _i * 8192), 16, 0, 0); } while (0)
; #define PG8_LDA(dst, b, h) do { _Pragma("unroll") for (int m = 0; m < 4; ++m) _Pragma("unroll") for (int k = 0; k < 2; ++k) dst[m][k] = *(const PG8_LAS bf16x8*)(lds + PG8_SA(b, h) + aoff + m * 2048 + k * 1024); } while (0)
; #define PG8_LDB(dst, b, h) do { _Pragma("unroll") for (int n = 0; n < 2; ++n) _Pragma("unroll") for (int k = 0; k < 2; ++k) dst[n][k] = *(const PG8_LAS bf16x8*)(lds + PG8_SB(b, h) + boff + n * 2048 + k * 1024); } while (0)
; #define PG8_MMA_NP(ai, bj, At, Bt) do { _Pragma("unroll") for (int m = 0; m < 4; ++m) _Pragma("unroll") for (int n = 0; n < 2; ++n) _Pragma("unroll") for (int k = 0; k < 2; ++k) \
;         acc[ai][bj][m][n] = __builtin_amdgcn_mfma_f32_16x16x32_bf16(Bt[n][k], At[m][k], acc[ai][bj][m][n], 0, 0, 0); } while (0)
; #define PG8_WAIT_V(n) asm volatile("s_waitcnt vmcnt(" #n ")" ::: "memory")
; #define PG8_WAIT_L(n) asm volatile("s_waitcnt lgkmcnt(" #n ")" ::: "memory")
; #define PG8_BAR __builtin_amdgcn_s_barrier()
; #define PG8_SCHED __builtin_amdgcn_sched_barrier(0)
; template <class Epi, class Sched, bool ALIGN_EPI = false, bool SP2 = false>
; __device__ __forceinline__ void gemm_phase(PG8_LAS unsigned char* lds, const Gemm g, const Sched& S, const Epi& E) {
;     ...
;             PG8_LDB(B0, 0, 0); PG8_LDB(B1, 0, 1); PG8_SCHED; PG8_LDA(At, 0, 0); PG8_STAGE(PG8_SA(1, 1), a1 + hstep, voffA);
;             PG8_WAIT_V(8); PG8_WAIT_L(0); PG8_BAR; __builtin_amdgcn_s_setprio(1); PG8_MMA_NP(0, 0, At, B0); PG8_MMA_NP(0, 1, At, B1); __builtin_amdgcn_s_setprio(0); PG8_BAR; PG8_SCHED;
;             PG8_LDA(At, 0, 1); PG8_STAGE(PG8_SB(0, 0), b2, voffB); PG8_STAGE(PG8_SB(0, 1), b2 + hstep, voffB); PG8_STAGE(PG8_SA(0, 0), a2, voffA);
;             PG8_WAIT_V(8); PG8_WAIT_L(0); PG8_BAR; __builtin_amdgcn_s_setprio(1); PG8_MMA_NP(1, 0, At, B0); PG8_MMA_NP(1, 1, At, B1); __builtin_amdgcn_s_setprio(0); PG8_BAR; PG8_SCHED;
.LBB0_1015:
	s_ashr_i32 s51, s50, 31
	s_lshl_b64 s[14:15], s[50:51], 19
	s_add_u32 s52, s90, s14
	s_addc_u32 s53, s91, s15
	s_and_b64 s[14:15], s[44:45], exec
	s_cselect_b32 s29, s53, s13
	s_cselect_b32 s30, s52, s12
	s_ashr_i32 s49, s48, 31
	s_lshl_b64 s[14:15], s[48:49], 19
	s_add_u32 s54, s31, s14
	s_addc_u32 s55, s40, s15
	s_and_b64 s[14:15], s[44:45], exec
	s_cselect_b32 s49, s55, s39
	s_cselect_b32 s51, s54, s38
	s_add_u32 s12, s12, 0x40080
	s_addc_u32 s13, s13, 0
	s_add_u32 s64, s38, 0x100
	s_addc_u32 s65, s39, 0
	s_mov_b32 s66, -2
	s_waitcnt lgkmcnt(0)
	s_add_u32 s14, s12, 0xfffc0080
	s_addc_u32 s15, s13, -1
	s_add_i32 s22, 0, 0x10000
	s_cmp_eq_u32 s66, 12
	s_cselect_b32 s39, s29, s15
	s_cselect_b32 s38, s30, s14
	v_add_u32_e32 v144, s22, v147
	s_cselect_b32 s15, s49, s65
	s_cselect_b32 s14, s51, s64
	s_add_i32 s67, 0, 0x14000
	ds_read_b128 v[140:143], v144
	ds_read_b128 v[150:153], v144 offset:1024
	ds_read_b128 v[154:157], v144 offset:2048
	ds_read_b128 v[158:161], v144 offset:3072
	v_add_u32_e32 v144, s67, v147
	ds_read_b128 v[178:181], v144
	ds_read_b128 v[182:185], v144 offset:1024
	ds_read_b128 v[186:189], v144 offset:2048
	ds_read_b128 v[202:205], v144 offset:3072
	v_lshl_add_u64 v[144:145], s[12:13], 0, v[136:137]
	s_add_i32 m0, s56, 0xc000
	ds_read_b128 v[206:209], v149
	ds_read_b128 v[210:213], v149 offset:1024
	ds_read_b128 v[214:217], v149 offset:2048
	ds_read_b128 v[218:221], v149 offset:3072
	ds_read_b128 v[222:225], v149 offset:4096
	ds_read_b128 v[226:229], v149 offset:5120
	ds_read_b128 v[230:233], v149 offset:6144
	ds_read_b128 v[234:237], v149 offset:7168
	global_load_lds_dwordx4 v[144:145], off
	v_lshl_add_u64 v[144:145], s[12:13], 0, v[138:139]
	s_add_i32 m0, s56, 0xe000
	s_nop 0
	global_load_lds_dwordx4 v[144:145], off
	s_waitcnt vmcnt(8)
	s_waitcnt lgkmcnt(0)
	s_barrier
	s_setprio 1
	s_waitcnt lgkmcnt(0)
	v_mfma_f32_16x16x32_bf16 v[126:129], v[140:143], v[206:209], 0
	v_mfma_f32_16x16x32_bf16 v[122:125], v[154:157], v[206:209], 0
	v_mfma_f32_16x16x32_bf16 v[110:113], v[140:143], v[214:217], 0
	v_mfma_f32_16x16x32_bf16 v[106:109], v[154:157], v[214:217], 0
	v_mfma_f32_16x16x32_bf16 v[94:97], v[140:143], v[222:225], 0
	v_mfma_f32_16x16x32_bf16 v[90:93], v[154:157], v[222:225], 0
	v_mfma_f32_16x16x32_bf16 v[78:81], v[140:143], v[230:233], 0
	v_mfma_f32_16x16x32_bf16 v[74:77], v[154:157], v[230:233], 0
	v_mfma_f32_16x16x32_bf16 v[118:121], v[178:181], v[206:209], 0
	v_mfma_f32_16x16x32_bf16 v[114:117], v[186:189], v[206:209], 0
	v_mfma_f32_16x16x32_bf16 v[102:105], v[178:181], v[214:217], 0
	v_mfma_f32_16x16x32_bf16 v[98:101], v[186:189], v[214:217], 0
	v_mfma_f32_16x16x32_bf16 v[86:89], v[178:181], v[222:225], 0
	v_mfma_f32_16x16x32_bf16 v[82:85], v[186:189], v[222:225], 0
	v_mfma_f32_16x16x32_bf16 v[70:73], v[178:181], v[230:233], 0
	v_mfma_f32_16x16x32_bf16 v[66:69], v[186:189], v[230:233], 0
	v_mfma_f32_16x16x32_bf16 v[126:129], v[150:153], v[210:213], v[126:129]
	v_mfma_f32_16x16x32_bf16 v[122:125], v[158:161], v[210:213], v[122:125]
	v_mfma_f32_16x16x32_bf16 v[110:113], v[150:153], v[218:221], v[110:113]
	v_mfma_f32_16x16x32_bf16 v[106:109], v[158:161], v[218:221], v[106:109]
	v_mfma_f32_16x16x32_bf16 v[94:97], v[150:153], v[226:229], v[94:97]
	v_mfma_f32_16x16x32_bf16 v[90:93], v[158:161], v[226:229], v[90:93]
	v_mfma_f32_16x16x32_bf16 v[78:81], v[150:153], v[234:237], v[78:81]
	v_mfma_f32_16x16x32_bf16 v[74:77], v[158:161], v[234:237], v[74:77]
	v_mfma_f32_16x16x32_bf16 v[118:121], v[182:185], v[210:213], v[118:121]
	v_mfma_f32_16x16x32_bf16 v[114:117], v[202:205], v[210:213], v[114:117]
	v_mfma_f32_16x16x32_bf16 v[102:105], v[182:185], v[218:221], v[102:105]
	v_mfma_f32_16x16x32_bf16 v[98:101], v[202:205], v[218:221], v[98:101]
	v_mfma_f32_16x16x32_bf16 v[86:89], v[182:185], v[226:229], v[86:89]
	v_mfma_f32_16x16x32_bf16 v[82:85], v[202:205], v[226:229], v[82:85]
	v_mfma_f32_16x16x32_bf16 v[70:73], v[182:185], v[234:237], v[70:73]
	v_mfma_f32_16x16x32_bf16 v[66:69], v[202:205], v[234:237], v[66:69]
	s_setprio 0
	s_barrier
	s_add_i32 s22, s22, s41
	v_lshl_add_u64 v[144:145], s[14:15], 0, v[0:1]
	s_mov_b32 m0, s22
	ds_read_b128 v[206:209], v149 offset:16384
	ds_read_b128 v[210:213], v149 offset:17408
	ds_read_b128 v[214:217], v149 offset:18432
	ds_read_b128 v[218:221], v149 offset:19456
	ds_read_b128 v[222:225], v149 offset:20480
	ds_read_b128 v[226:229], v149 offset:21504
	ds_read_b128 v[230:233], v149 offset:22528
	ds_read_b128 v[234:237], v149 offset:23552
	global_load_lds_dwordx4 v[144:145], off
	s_add_i32 m0, s22, 0x2000
	s_add_u32 s22, s14, 0x40000
	v_lshl_add_u64 v[162:163], s[14:15], 0, v[130:131]
	s_addc_u32 s23, s15, 0
	s_add_i32 s67, s67, s41
	global_load_lds_dwordx4 v[162:163], off
	v_lshl_add_u64 v[190:191], s[22:23], 0, v[0:1]
	s_mov_b32 m0, s67
	v_lshl_add_u64 v[238:239], s[38:39], 0, v[132:133]
	global_load_lds_dwordx4 v[190:191], off
	v_lshl_add_u64 v[190:191], s[22:23], 0, v[130:131]
	s_add_i32 m0, s67, 0x2000
	s_nop 0
	global_load_lds_dwordx4 v[190:191], off
	v_lshl_add_u64 v[190:191], s[38:39], 0, v[134:135]
	s_mov_b32 m0, s56
	s_nop 0
	global_load_lds_dwordx4 v[190:191], off
	s_mov_b32 m0, s57
	s_nop 0
	global_load_lds_dwordx4 v[238:239], off
	s_waitcnt vmcnt(8)
	s_waitcnt lgkmcnt(0)
	s_barrier
; #define PG8_STAGE(bufoff, gbase, voff) do { _Pragma("unroll") for (int _i = 0; _i < 2; ++_i) \
;         __builtin_amdgcn_global_load_lds((const unsigned*)((const char*)(gbase) + (voff)[_i]), (PG8_LAS unsigned*)(lds + (bufoff) + ldsw + _i * 8192), 16, 0, 0); } while (0)
; #define PG8_LDA(dst, b, h) do { _Pragma("unroll") for (int m = 0; m < 4; ++m) _Pragma("unroll") for (int k = 0; k < 2; ++k) dst[m][k] = *(const PG8_LAS bf16x8*)(lds + PG8_SA(b, h) + aoff + m * 2048 + k * 1024); } while (0)
; #define PG8_LDB(dst, b, h) do { _Pragma("unroll") for (int n = 0; n < 2; ++n) _Pragma("unroll") for (int k = 0; k < 2; ++k) dst[n][k] = *(const PG8_LAS bf16x8*)(lds + PG8_SB(b, h) + boff + n * 2048 + k * 1024); } while (0)
; #define PG8_MMA_NP(ai, bj, At, Bt) do { _Pragma("unroll") for (int m = 0; m < 4; ++m) _Pragma("unroll") for (int n = 0; n < 2; ++n) _Pragma("unroll") for (int k = 0; k < 2; ++k) \
;         acc[ai][bj][m][n] = __builtin_amdgcn_mfma_f32_16x16x32_bf16(Bt[n][k], At[m][k], acc[ai][bj][m][n], 0, 0, 0); } while (0)
; #define PG8_WAIT_V(n) asm volatile("s_waitcnt vmcnt(" #n ")" ::: "memory")
; #define PG8_WAIT_L(n) asm volatile("s_waitcnt lgkmcnt(" #n ")" ::: "memory")
; #define PG8_BAR __builtin_amdgcn_s_barrier()
; #define PG8_SCHED __builtin_amdgcn_sched_barrier(0)
; template <class Epi, class Sched, bool ALIGN_EPI = false, bool SP2 = false>
; __device__ __forceinline__ void gemm_phase(PG8_LAS unsigned char* lds, const Gemm g, const Sched& S, const Epi& E) {
;     ...
;             PG8_WAIT_V(8); PG8_WAIT_L(0); PG8_BAR; __builtin_amdgcn_s_setprio(1); PG8_MMA_NP(0, 0, At, B0); PG8_MMA_NP(0, 1, At, B1); __builtin_amdgcn_s_setprio(0); PG8_BAR; PG8_SCHED;
;             PG8_LDA(At, 0, 1); PG8_STAGE(PG8_SB(0, 0), b2, voffB); PG8_STAGE(PG8_SB(0, 1), b2 + hstep, voffB); PG8_STAGE(PG8_SA(0, 0), a2, voffA);
;             PG8_WAIT_V(8); PG8_WAIT_L(0); PG8_BAR; __builtin_amdgcn_s_setprio(1); PG8_MMA_NP(1, 0, At, B0); PG8_MMA_NP(1, 1, At, B1); __builtin_amdgcn_s_setprio(0); PG8_BAR; PG8_SCHED;
;             PG8_LDB(B0, 1, 0); PG8_LDB(B1, 1, 1); PG8_SCHED; PG8_LDA(At, 1, 0); PG8_STAGE(PG8_SA(0, 1), a2 + hstep, voffA);
;             PG8_WAIT_V(8); PG8_WAIT_L(0); PG8_BAR; __builtin_amdgcn_s_setprio(1); PG8_MMA_NP(0, 0, At, B0); PG8_MMA_NP(0, 1, At, B1); __builtin_amdgcn_s_setprio(0); PG8_BAR; PG8_SCHED;
	s_setprio 1
	s_waitcnt lgkmcnt(0)
	v_mfma_f32_16x16x32_bf16 v[62:65], v[140:143], v[206:209], 0
	v_mfma_f32_16x16x32_bf16 v[58:61], v[154:157], v[206:209], 0
	v_mfma_f32_16x16x32_bf16 v[46:49], v[140:143], v[214:217], 0
	v_mfma_f32_16x16x32_bf16 v[42:45], v[154:157], v[214:217], 0
	v_mfma_f32_16x16x32_bf16 v[30:33], v[140:143], v[222:225], 0
	v_mfma_f32_16x16x32_bf16 v[26:29], v[154:157], v[222:225], 0
	v_mfma_f32_16x16x32_bf16 v[14:17], v[140:143], v[230:233], 0
	v_mfma_f32_16x16x32_bf16 v[10:13], v[154:157], v[230:233], 0
	v_mfma_f32_16x16x32_bf16 v[54:57], v[178:181], v[206:209], 0
	v_mfma_f32_16x16x32_bf16 v[50:53], v[186:189], v[206:209], 0
	v_mfma_f32_16x16x32_bf16 v[38:41], v[178:181], v[214:217], 0
	v_mfma_f32_16x16x32_bf16 v[34:37], v[186:189], v[214:217], 0
	v_mfma_f32_16x16x32_bf16 v[22:25], v[178:181], v[222:225], 0
	v_mfma_f32_16x16x32_bf16 v[18:21], v[186:189], v[222:225], 0
	v_mfma_f32_16x16x32_bf16 v[6:9], v[178:181], v[230:233], 0
	v_mfma_f32_16x16x32_bf16 v[2:5], v[186:189], v[230:233], 0
	v_mfma_f32_16x16x32_bf16 v[62:65], v[150:153], v[210:213], v[62:65]
	v_mfma_f32_16x16x32_bf16 v[58:61], v[158:161], v[210:213], v[58:61]
	v_mfma_f32_16x16x32_bf16 v[46:49], v[150:153], v[218:221], v[46:49]
	v_mfma_f32_16x16x32_bf16 v[42:45], v[158:161], v[218:221], v[42:45]
	v_mfma_f32_16x16x32_bf16 v[30:33], v[150:153], v[226:229], v[30:33]
	v_mfma_f32_16x16x32_bf16 v[26:29], v[158:161], v[226:229], v[26:29]
	v_mfma_f32_16x16x32_bf16 v[14:17], v[150:153], v[234:237], v[14:17]
	v_mfma_f32_16x16x32_bf16 v[10:13], v[158:161], v[234:237], v[10:13]
	v_mfma_f32_16x16x32_bf16 v[54:57], v[182:185], v[210:213], v[54:57]
	v_mfma_f32_16x16x32_bf16 v[50:53], v[202:205], v[210:213], v[50:53]
	v_mfma_f32_16x16x32_bf16 v[38:41], v[182:185], v[218:221], v[38:41]
	v_mfma_f32_16x16x32_bf16 v[34:37], v[202:205], v[218:221], v[34:37]
	v_mfma_f32_16x16x32_bf16 v[22:25], v[182:185], v[226:229], v[22:25]
	v_mfma_f32_16x16x32_bf16 v[18:21], v[202:205], v[226:229], v[18:21]
	v_mfma_f32_16x16x32_bf16 v[6:9], v[182:185], v[234:237], v[6:9]
	v_mfma_f32_16x16x32_bf16 v[2:5], v[202:205], v[234:237], v[2:5]
	s_setprio 0
	s_barrier
	s_add_i32 s67, 0, 0x18000
	s_add_i32 s68, 0, 0x1c000
	v_add_u32_e32 v158, s67, v147
	v_add_u32_e32 v202, s68, v147
	ds_read_b128 v[140:143], v158
	ds_read_b128 v[150:153], v158 offset:1024
	ds_read_b128 v[154:157], v158 offset:2048
	ds_read_b128 v[158:161], v158 offset:3072
	ds_read_b128 v[178:181], v202
	ds_read_b128 v[182:185], v202 offset:1024
	ds_read_b128 v[186:189], v202 offset:2048
	ds_read_b128 v[202:205], v202 offset:3072
	s_add_u32 s22, s38, 0x40000
	s_addc_u32 s23, s39, 0
	s_mov_b32 m0, s58
	v_lshl_add_u64 v[240:241], s[22:23], 0, v[134:135]
	ds_read_b128 v[206:209], v149 offset:32768
	ds_read_b128 v[210:213], v149 offset:33792
	ds_read_b128 v[214:217], v149 offset:34816
	ds_read_b128 v[218:221], v149 offset:35840
	ds_read_b128 v[222:225], v149 offset:36864
	ds_read_b128 v[226:229], v149 offset:37888
	ds_read_b128 v[230:233], v149 offset:38912
	ds_read_b128 v[234:237], v149 offset:39936
	global_load_lds_dwordx4 v[240:241], off
	v_lshl_add_u64 v[240:241], s[22:23], 0, v[132:133]
	s_mov_b32 m0, s59
	s_nop 0
	global_load_lds_dwordx4 v[240:241], off
	s_waitcnt vmcnt(8)
	s_waitcnt lgkmcnt(0)
	s_barrier
	s_setprio 1
	s_waitcnt lgkmcnt(0)
	v_mfma_f32_16x16x32_bf16 v[126:129], v[140:143], v[206:209], v[126:129]
	v_mfma_f32_16x16x32_bf16 v[122:125], v[154:157], v[206:209], v[122:125]
	v_mfma_f32_16x16x32_bf16 v[110:113], v[140:143], v[214:217], v[110:113]
	v_mfma_f32_16x16x32_bf16 v[106:109], v[154:157], v[214:217], v[106:109]
	v_mfma_f32_16x16x32_bf16 v[94:97], v[140:143], v[222:225], v[94:97]
	v_mfma_f32_16x16x32_bf16 v[90:93], v[154:157], v[222:225], v[90:93]
	v_mfma_f32_16x16x32_bf16 v[78:81], v[140:143], v[230:233], v[78:81]
	v_mfma_f32_16x16x32_bf16 v[74:77], v[154:157], v[230:233], v[74:77]
	v_mfma_f32_16x16x32_bf16 v[118:121], v[178:181], v[206:209], v[118:121]
	v_mfma_f32_16x16x32_bf16 v[114:117], v[186:189], v[206:209], v[114:117]
	v_mfma_f32_16x16x32_bf16 v[102:105], v[178:181], v[214:217], v[102:105]
	v_mfma_f32_16x16x32_bf16 v[98:101], v[186:189], v[214:217], v[98:101]
	v_mfma_f32_16x16x32_bf16 v[86:89], v[178:181], v[222:225], v[86:89]
	v_mfma_f32_16x16x32_bf16 v[82:85], v[186:189], v[222:225], v[82:85]
	v_mfma_f32_16x16x32_bf16 v[70:73], v[178:181], v[230:233], v[70:73]
	v_mfma_f32_16x16x32_bf16 v[66:69], v[186:189], v[230:233], v[66:69]
	v_mfma_f32_16x16x32_bf16 v[126:129], v[150:153], v[210:213], v[126:129]
	v_mfma_f32_16x16x32_bf16 v[122:125], v[158:161], v[210:213], v[122:125]
	v_mfma_f32_16x16x32_bf16 v[110:113], v[150:153], v[218:221], v[110:113]
	v_mfma_f32_16x16x32_bf16 v[106:109], v[158:161], v[218:221], v[106:109]
	v_mfma_f32_16x16x32_bf16 v[94:97], v[150:153], v[226:229], v[94:97]
	v_mfma_f32_16x16x32_bf16 v[90:93], v[158:161], v[226:229], v[90:93]
	v_mfma_f32_16x16x32_bf16 v[78:81], v[150:153], v[234:237], v[78:81]
	v_mfma_f32_16x16x32_bf16 v[74:77], v[158:161], v[234:237], v[74:77]
	v_mfma_f32_16x16x32_bf16 v[118:121], v[182:185], v[210:213], v[118:121]
	v_mfma_f32_16x16x32_bf16 v[114:117], v[202:205], v[210:213], v[114:117]
	v_mfma_f32_16x16x32_bf16 v[102:105], v[182:185], v[218:221], v[102:105]
	v_mfma_f32_16x16x32_bf16 v[98:101], v[202:205], v[218:221], v[98:101]
	v_mfma_f32_16x16x32_bf16 v[86:89], v[182:185], v[226:229], v[86:89]
	v_mfma_f32_16x16x32_bf16 v[82:85], v[202:205], v[226:229], v[82:85]
	v_mfma_f32_16x16x32_bf16 v[70:73], v[182:185], v[234:237], v[70:73]
	v_mfma_f32_16x16x32_bf16 v[66:69], v[202:205], v[234:237], v[66:69]
	s_setprio 0
	s_barrier
; #define PG8_STAGE(bufoff, gbase, voff) do { _Pragma("unroll") for (int _i = 0; _i < 2; ++_i) \
;         __builtin_amdgcn_global_load_lds((const unsigned*)((const char*)(gbase) + (voff)[_i]), (PG8_LAS unsigned*)(lds + (bufoff) + ldsw + _i * 8192), 16, 0, 0); } while (0)
; #define PG8_LDA(dst, b, h) do { _Pragma("unroll") for (int m = 0; m < 4; ++m) _Pragma("unroll") for (int k = 0; k < 2; ++k) dst[m][k] = *(const PG8_LAS bf16x8*)(lds + PG8_SA(b, h) + aoff + m * 2048 + k * 1024); } while (0)
; #define PG8_MMA_NP(ai, bj, At, Bt) do { _Pragma("unroll") for (int m = 0; m < 4; ++m) _Pragma("unroll") for (int n = 0; n < 2; ++n) _Pragma("unroll") for (int k = 0; k < 2; ++k) \
;         acc[ai][bj][m][n] = __builtin_amdgcn_mfma_f32_16x16x32_bf16(Bt[n][k], At[m][k], acc[ai][bj][m][n], 0, 0, 0); } while (0)
; #define PG8_WAIT_V(n) asm volatile("s_waitcnt vmcnt(" #n ")" ::: "memory")
; #define PG8_WAIT_L(n) asm volatile("s_waitcnt lgkmcnt(" #n ")" ::: "memory")
; #define PG8_BAR __builtin_amdgcn_s_barrier()
; #define PG8_SCHED __builtin_amdgcn_sched_barrier(0)
; template <class Epi, class Sched, bool ALIGN_EPI = false, bool SP2 = false>
; __device__ __forceinline__ void gemm_phase(PG8_LAS unsigned char* lds, const Gemm g, const Sched& S, const Epi& E) {
;     ...
;         for (int t = 0; t < nt; t += 2) {
;     ...
;             PG8_LDA(At, 1, 1); PG8_STAGE(PG8_SB(1, 0), b3, voffB); PG8_STAGE(PG8_SB(1, 1), b3 + hstep, voffB); PG8_STAGE(PG8_SA(1, 0), a3, voffA);
;             PG8_WAIT_V(8); PG8_WAIT_L(0); PG8_BAR; __builtin_amdgcn_s_setprio(1); PG8_MMA_NP(1, 0, At, B0); PG8_MMA_NP(1, 1, At, B1); __builtin_amdgcn_s_setprio(0); PG8_BAR; PG8_SCHED;
	s_add_i32 s22, s67, s41
	v_lshl_add_u64 v[144:145], v[144:145], 0, s[20:21]
	s_mov_b32 m0, s22
	ds_read_b128 v[206:209], v149 offset:49152
	ds_read_b128 v[210:213], v149 offset:50176
	ds_read_b128 v[214:217], v149 offset:51200
	ds_read_b128 v[218:221], v149 offset:52224
	ds_read_b128 v[222:225], v149 offset:53248
	ds_read_b128 v[226:229], v149 offset:54272
	ds_read_b128 v[230:233], v149 offset:55296
	ds_read_b128 v[234:237], v149 offset:56320
	global_load_lds_dwordx4 v[144:145], off
	s_add_i32 m0, s22, 0x2000
	s_add_u32 s14, s14, 0x40080
	v_lshl_add_u64 v[144:145], v[162:163], 0, s[20:21]
	s_addc_u32 s15, s15, 0
	s_add_i32 s22, s68, s41
	global_load_lds_dwordx4 v[144:145], off
	v_lshl_add_u64 v[144:145], s[14:15], 0, v[0:1]
	s_mov_b32 m0, s22
	s_nop 0
	global_load_lds_dwordx4 v[144:145], off
	v_lshl_add_u64 v[144:145], s[14:15], 0, v[130:131]
	s_add_i32 m0, s22, 0x2000
	s_nop 0
	global_load_lds_dwordx4 v[144:145], off
	v_lshl_add_u64 v[144:145], v[190:191], 0, s[20:21]
	s_mov_b32 m0, s61
	s_nop 0
	global_load_lds_dwordx4 v[144:145], off
	v_lshl_add_u64 v[144:145], v[238:239], 0, s[20:21]
	s_mov_b32 m0, s62
	s_nop 0
	global_load_lds_dwordx4 v[144:145], off
	s_waitcnt vmcnt(8)
	s_waitcnt lgkmcnt(0)
	s_barrier
	s_setprio 1
	s_waitcnt lgkmcnt(0)
	v_mfma_f32_16x16x32_bf16 v[62:65], v[140:143], v[206:209], v[62:65]
	v_mfma_f32_16x16x32_bf16 v[58:61], v[154:157], v[206:209], v[58:61]
	v_mfma_f32_16x16x32_bf16 v[46:49], v[140:143], v[214:217], v[46:49]
	v_mfma_f32_16x16x32_bf16 v[42:45], v[154:157], v[214:217], v[42:45]
	v_mfma_f32_16x16x32_bf16 v[30:33], v[140:143], v[222:225], v[30:33]
	v_mfma_f32_16x16x32_bf16 v[26:29], v[154:157], v[222:225], v[26:29]
	v_mfma_f32_16x16x32_bf16 v[14:17], v[140:143], v[230:233], v[14:17]
	v_mfma_f32_16x16x32_bf16 v[10:13], v[154:157], v[230:233], v[10:13]
	v_mfma_f32_16x16x32_bf16 v[54:57], v[178:181], v[206:209], v[54:57]
	v_mfma_f32_16x16x32_bf16 v[50:53], v[186:189], v[206:209], v[50:53]
	v_mfma_f32_16x16x32_bf16 v[38:41], v[178:181], v[214:217], v[38:41]
	v_mfma_f32_16x16x32_bf16 v[34:37], v[186:189], v[214:217], v[34:37]
	v_mfma_f32_16x16x32_bf16 v[22:25], v[178:181], v[222:225], v[22:25]
	v_mfma_f32_16x16x32_bf16 v[18:21], v[186:189], v[222:225], v[18:21]
	v_mfma_f32_16x16x32_bf16 v[6:9], v[178:181], v[230:233], v[6:9]
	v_mfma_f32_16x16x32_bf16 v[2:5], v[186:189], v[230:233], v[2:5]
	v_mfma_f32_16x16x32_bf16 v[62:65], v[150:153], v[210:213], v[62:65]
	v_mfma_f32_16x16x32_bf16 v[58:61], v[158:161], v[210:213], v[58:61]
	v_mfma_f32_16x16x32_bf16 v[46:49], v[150:153], v[218:221], v[46:49]
	v_mfma_f32_16x16x32_bf16 v[42:45], v[158:161], v[218:221], v[42:45]
	v_mfma_f32_16x16x32_bf16 v[30:33], v[150:153], v[226:229], v[30:33]
	v_mfma_f32_16x16x32_bf16 v[26:29], v[158:161], v[226:229], v[26:29]
	v_mfma_f32_16x16x32_bf16 v[14:17], v[150:153], v[234:237], v[14:17]
	v_mfma_f32_16x16x32_bf16 v[10:13], v[158:161], v[234:237], v[10:13]
	v_mfma_f32_16x16x32_bf16 v[54:57], v[182:185], v[210:213], v[54:57]
	v_mfma_f32_16x16x32_bf16 v[50:53], v[202:205], v[210:213], v[50:53]
	v_mfma_f32_16x16x32_bf16 v[38:41], v[182:185], v[218:221], v[38:41]
	v_mfma_f32_16x16x32_bf16 v[34:37], v[202:205], v[218:221], v[34:37]
	v_mfma_f32_16x16x32_bf16 v[22:25], v[182:185], v[226:229], v[22:25]
	v_mfma_f32_16x16x32_bf16 v[18:21], v[202:205], v[226:229], v[18:21]
	v_mfma_f32_16x16x32_bf16 v[6:9], v[182:185], v[234:237], v[6:9]
	v_mfma_f32_16x16x32_bf16 v[2:5], v[202:205], v[234:237], v[2:5]
	s_setprio 0
	s_barrier
	s_add_i32 s66, s66, 2
	s_add_u32 s12, s12, 0x100
	s_addc_u32 s13, s13, 0
	s_add_u32 s64, s64, 0x100
	s_addc_u32 s65, s65, 0
	s_cmp_gt_u32 s66, 13
	s_cbranch_scc0 .LBB0_1016
	s_branch .Lkexit_4
	.p2align 3

; #define PG8_STAGE(bufoff, gbase, voff) do { _Pragma("unroll") for (int _i = 0; _i < 2; ++_i) \
;         __builtin_amdgcn_global_load_lds((const unsigned*)((const char*)(gbase) + (voff)[_i]), (PG8_LAS unsigned*)(lds + (bufoff) + ldsw + _i * 8192), 16, 0, 0); } while (0)
; #define PG8_LDA(dst, b, h) do { _Pragma("unroll") for (int m = 0; m < 4; ++m) _Pragma("unroll") for (int k = 0; k < 2; ++k) dst[m][k] = *(const PG8_LAS bf16x8*)(lds + PG8_SA(b, h) + aoff + m * 2048 + k * 1024); } while (0)
; #define PG8_LDB(dst, b, h) do { _Pragma("unroll") for (int n = 0; n < 2; ++n) _Pragma("unroll") for (int k = 0; k < 2; ++k) dst[n][k] = *(const PG8_LAS bf16x8*)(lds + PG8_SB(b, h) + boff + n * 2048 + k * 1024); } while (0)
; #define PG8_MMA_NP(ai, bj, At, Bt) do { _Pragma("unroll") for (int m = 0; m < 4; ++m) _Pragma("unroll") for (int n = 0; n < 2; ++n) _Pragma("unroll") for (int k = 0; k < 2; ++k) \
;         acc[ai][bj][m][n] = __builtin_amdgcn_mfma_f32_16x16x32_bf16(Bt[n][k], At[m][k], acc[ai][bj][m][n], 0, 0, 0); } while (0)
; template <class Epi, class Sched, bool ALIGN_EPI = false, bool SP2 = false>
; __device__ __forceinline__ void gemm_phase(PG8_LAS unsigned char* lds, const Gemm g, const Sched& S, const Epi& E) {
;     ...
;         const bool has_next = S.next(ui + 1, nxt);
;         const char* nA = has_next ? (const char*)g.A + (size_t)nxt.pm * tstep : cA; const char* nB = has_next ? (const char*)g.Bt + (size_t)nxt.pn * tstep : cB;
;         for (int t = 0; t < nt; t += 2) {
;             const bool last = (t == nt - 2);
;             const char* a1 = cA + (size_t)(t + 1) * kstep;
;             const char* a2 = last ? nA : cA + (size_t)(t + 2) * kstep; const char* b2 = last ? nB : cB + (size_t)(t + 2) * kstep;
;             const char* a3 = a2 + kstep; const char* b3 = b2 + kstep;
;             if (last && has_next) S.a_ready(nxt);
;             if constexpr (SP2) {
;             PG8_LDB(B0, 0, 0); PG8_LDB(B1, 0, 1); PG8_SCHED; PG8_LDA(At, 0, 0); PG8_STAGE(PG8_SA(1, 1), a1 + hstep, voffA);
;             PG8_WAIT_V(8); PG8_WAIT_L(0); PG8_BAR; __builtin_amdgcn_s_setprio(1); PG8_MMA_NP(0, 0, At, B0); PG8_MMA_NP(0, 1, At, B1); __builtin_amdgcn_s_setprio(0); PG8_BAR; PG8_SCHED;
;             PG8_LDA(At, 0, 1); PG8_STAGE(PG8_SB(0, 0), b2, voffB); PG8_STAGE(PG8_SB(0, 1), b2 + hstep, voffB); PG8_STAGE(PG8_SA(0, 0), a2, voffA);
.LBB0_1121:
	s_ashr_i32 s49, s48, 31
	s_lshl_b64 s[14:15], s[48:49], 19
	s_add_u32 s50, s86, s14
	s_addc_u32 s51, s87, s15
	s_and_b64 s[14:15], s[38:39], exec
	s_cselect_b32 s49, s51, s3
	s_cselect_b32 s59, s50, s2
	s_ashr_i32 s47, s46, 31
	s_lshl_b64 s[14:15], s[46:47], 19
	s_add_u32 s52, s8, s14
	s_addc_u32 s53, s10, s15
	s_and_b64 s[14:15], s[38:39], exec
	s_cselect_b32 s47, s53, s13
	s_cselect_b32 s60, s52, s12
	s_add_u32 s2, s2, 0x40080
	s_addc_u32 s3, s3, 0
	s_add_u32 s61, s12, 0x100
	s_addc_u32 s62, s13, 0
	s_mov_b32 s63, -2
	s_add_u32 s12, s2, 0xfffc0080
	s_addc_u32 s13, s3, -1
	s_add_i32 s22, 0, 0x10000
	s_cmp_eq_u32 s63, 12
	s_cselect_b32 s15, s49, s13
	s_cselect_b32 s14, s59, s12
	s_cselect_b32 s13, s47, s62
	s_cselect_b32 s12, s60, s61
	s_add_i32 s64, 0, 0x14000
	v_add_u32_e32 v154, s22, v183
	v_add_u32_e32 v162, s64, v183
	ds_read_b128 v[130:133], v154
	ds_read_b128 v[146:149], v154 offset:1024
	ds_read_b128 v[150:153], v154 offset:2048
	ds_read_b128 v[154:157], v154 offset:3072
	ds_read_b128 v[158:161], v162
	ds_read_b128 v[178:181], v162 offset:1024
	ds_read_b128 v[186:189], v162 offset:2048
	ds_read_b128 v[202:205], v162 offset:3072
	v_lshl_add_u64 v[162:163], s[2:3], 0, v[142:143]
	s_add_i32 m0, s30, 0xc000
	ds_read_b128 v[206:209], v185
	ds_read_b128 v[210:213], v185 offset:1024
	ds_read_b128 v[214:217], v185 offset:2048
	ds_read_b128 v[218:221], v185 offset:3072
	ds_read_b128 v[222:225], v185 offset:4096
	ds_read_b128 v[226:229], v185 offset:5120
	ds_read_b128 v[230:233], v185 offset:6144
	ds_read_b128 v[234:237], v185 offset:7168
	global_load_lds_dwordx4 v[162:163], off
	v_lshl_add_u64 v[162:163], s[2:3], 0, v[144:145]
	s_add_i32 m0, s30, 0xe000
	s_nop 0
	global_load_lds_dwordx4 v[162:163], off
	s_waitcnt vmcnt(8)
	s_waitcnt lgkmcnt(0)
	s_barrier
	s_setprio 1
	s_waitcnt lgkmcnt(0)
	v_mfma_f32_16x16x32_bf16 v[126:129], v[130:133], v[206:209], 0
	v_mfma_f32_16x16x32_bf16 v[118:121], v[150:153], v[206:209], 0
	v_mfma_f32_16x16x32_bf16 v[110:113], v[130:133], v[214:217], 0
	v_mfma_f32_16x16x32_bf16 v[102:105], v[150:153], v[214:217], 0
	v_mfma_f32_16x16x32_bf16 v[94:97], v[130:133], v[222:225], 0
	v_mfma_f32_16x16x32_bf16 v[86:89], v[150:153], v[222:225], 0
	v_mfma_f32_16x16x32_bf16 v[78:81], v[130:133], v[230:233], 0
	v_mfma_f32_16x16x32_bf16 v[70:73], v[150:153], v[230:233], 0
	v_mfma_f32_16x16x32_bf16 v[122:125], v[158:161], v[206:209], 0
	v_mfma_f32_16x16x32_bf16 v[114:117], v[186:189], v[206:209], 0
	v_mfma_f32_16x16x32_bf16 v[106:109], v[158:161], v[214:217], 0
	v_mfma_f32_16x16x32_bf16 v[98:101], v[186:189], v[214:217], 0
	v_mfma_f32_16x16x32_bf16 v[90:93], v[158:161], v[222:225], 0
	v_mfma_f32_16x16x32_bf16 v[82:85], v[186:189], v[222:225], 0
	v_mfma_f32_16x16x32_bf16 v[74:77], v[158:161], v[230:233], 0
	v_mfma_f32_16x16x32_bf16 v[66:69], v[186:189], v[230:233], 0
	v_mfma_f32_16x16x32_bf16 v[126:129], v[146:149], v[210:213], v[126:129]
	v_mfma_f32_16x16x32_bf16 v[118:121], v[154:157], v[210:213], v[118:121]
	v_mfma_f32_16x16x32_bf16 v[110:113], v[146:149], v[218:221], v[110:113]
	v_mfma_f32_16x16x32_bf16 v[102:105], v[154:157], v[218:221], v[102:105]
	v_mfma_f32_16x16x32_bf16 v[94:97], v[146:149], v[226:229], v[94:97]
	v_mfma_f32_16x16x32_bf16 v[86:89], v[154:157], v[226:229], v[86:89]
	v_mfma_f32_16x16x32_bf16 v[78:81], v[146:149], v[234:237], v[78:81]
	v_mfma_f32_16x16x32_bf16 v[70:73], v[154:157], v[234:237], v[70:73]
	v_mfma_f32_16x16x32_bf16 v[122:125], v[178:181], v[210:213], v[122:125]
	v_mfma_f32_16x16x32_bf16 v[114:117], v[202:205], v[210:213], v[114:117]
	v_mfma_f32_16x16x32_bf16 v[106:109], v[178:181], v[218:221], v[106:109]
	v_mfma_f32_16x16x32_bf16 v[98:101], v[202:205], v[218:221], v[98:101]
	v_mfma_f32_16x16x32_bf16 v[90:93], v[178:181], v[226:229], v[90:93]
	v_mfma_f32_16x16x32_bf16 v[82:85], v[202:205], v[226:229], v[82:85]
	v_mfma_f32_16x16x32_bf16 v[74:77], v[178:181], v[234:237], v[74:77]
	v_mfma_f32_16x16x32_bf16 v[66:69], v[202:205], v[234:237], v[66:69]
	s_setprio 0
	s_barrier
	s_add_i32 s22, s22, s29
	v_lshl_add_u64 v[162:163], s[12:13], 0, v[0:1]
	s_mov_b32 m0, s22
	ds_read_b128 v[206:209], v185 offset:16384
	ds_read_b128 v[210:213], v185 offset:17408
	ds_read_b128 v[214:217], v185 offset:18432
	ds_read_b128 v[218:221], v185 offset:19456
	ds_read_b128 v[222:225], v185 offset:20480
	ds_read_b128 v[226:229], v185 offset:21504
	ds_read_b128 v[230:233], v185 offset:22528
	ds_read_b128 v[234:237], v185 offset:23552
	global_load_lds_dwordx4 v[162:163], off
	s_add_i32 m0, s22, 0x2000
	s_add_u32 s22, s12, 0x40000
	v_lshl_add_u64 v[190:191], s[12:13], 0, v[134:135]
	s_addc_u32 s23, s13, 0
	s_add_i32 s64, s64, s29
	global_load_lds_dwordx4 v[190:191], off
	v_lshl_add_u64 v[238:239], s[22:23], 0, v[0:1]
	s_mov_b32 m0, s64
	v_lshl_add_u64 v[240:241], s[14:15], 0, v[136:137]
	global_load_lds_dwordx4 v[238:239], off
	v_lshl_add_u64 v[238:239], s[22:23], 0, v[134:135]
	s_add_i32 m0, s64, 0x2000
	s_nop 0
	global_load_lds_dwordx4 v[238:239], off
	v_lshl_add_u64 v[238:239], s[14:15], 0, v[138:139]
	s_mov_b32 m0, s30
	s_nop 0
	global_load_lds_dwordx4 v[238:239], off
	s_mov_b32 m0, s31
	s_nop 0
	global_load_lds_dwordx4 v[240:241], off
	s_waitcnt vmcnt(8)
	s_waitcnt lgkmcnt(0)
	s_barrier
; #define PG8_STAGE(bufoff, gbase, voff) do { _Pragma("unroll") for (int _i = 0; _i < 2; ++_i) \
;         __builtin_amdgcn_global_load_lds((const unsigned*)((const char*)(gbase) + (voff)[_i]), (PG8_LAS unsigned*)(lds + (bufoff) + ldsw + _i * 8192), 16, 0, 0); } while (0)
; #define PG8_LDA(dst, b, h) do { _Pragma("unroll") for (int m = 0; m < 4; ++m) _Pragma("unroll") for (int k = 0; k < 2; ++k) dst[m][k] = *(const PG8_LAS bf16x8*)(lds + PG8_SA(b, h) + aoff + m * 2048 + k * 1024); } while (0)
; #define PG8_LDB(dst, b, h) do { _Pragma("unroll") for (int n = 0; n < 2; ++n) _Pragma("unroll") for (int k = 0; k < 2; ++k) dst[n][k] = *(const PG8_LAS bf16x8*)(lds + PG8_SB(b, h) + boff + n * 2048 + k * 1024); } while (0)
; #define PG8_MMA_NP(ai, bj, At, Bt) do { _Pragma("unroll") for (int m = 0; m < 4; ++m) _Pragma("unroll") for (int n = 0; n < 2; ++n) _Pragma("unroll") for (int k = 0; k < 2; ++k) \
;         acc[ai][bj][m][n] = __builtin_amdgcn_mfma_f32_16x16x32_bf16(Bt[n][k], At[m][k], acc[ai][bj][m][n], 0, 0, 0); } while (0)
; #define PG8_WAIT_V(n) asm volatile("s_waitcnt vmcnt(" #n ")" ::: "memory")
; #define PG8_WAIT_L(n) asm volatile("s_waitcnt lgkmcnt(" #n ")" ::: "memory")
; #define PG8_BAR __builtin_amdgcn_s_barrier()
; #define PG8_SCHED __builtin_amdgcn_sched_barrier(0)
; template <class Epi, class Sched, bool ALIGN_EPI = false, bool SP2 = false>
; __device__ __forceinline__ void gemm_phase(PG8_LAS unsigned char* lds, const Gemm g, const Sched& S, const Epi& E) {
;     ...
;             PG8_WAIT_V(8); PG8_WAIT_L(0); PG8_BAR; __builtin_amdgcn_s_setprio(1); PG8_MMA_NP(1, 0, At, B0); PG8_MMA_NP(1, 1, At, B1); __builtin_amdgcn_s_setprio(0); PG8_BAR; PG8_SCHED;
;             PG8_LDB(B0, 1, 0); PG8_LDB(B1, 1, 1); PG8_SCHED; PG8_LDA(At, 1, 0); PG8_STAGE(PG8_SA(0, 1), a2 + hstep, voffA);
;             PG8_WAIT_V(8); PG8_WAIT_L(0); PG8_BAR; __builtin_amdgcn_s_setprio(1); PG8_MMA_NP(0, 0, At, B0); PG8_MMA_NP(0, 1, At, B1); __builtin_amdgcn_s_setprio(0); PG8_BAR; PG8_SCHED;
	s_setprio 1
	s_waitcnt lgkmcnt(0)
	v_mfma_f32_16x16x32_bf16 v[62:65], v[130:133], v[206:209], 0
	v_mfma_f32_16x16x32_bf16 v[54:57], v[150:153], v[206:209], 0
	v_mfma_f32_16x16x32_bf16 v[46:49], v[130:133], v[214:217], 0
	v_mfma_f32_16x16x32_bf16 v[38:41], v[150:153], v[214:217], 0
	v_mfma_f32_16x16x32_bf16 v[30:33], v[130:133], v[222:225], 0
	v_mfma_f32_16x16x32_bf16 v[22:25], v[150:153], v[222:225], 0
	v_mfma_f32_16x16x32_bf16 v[14:17], v[130:133], v[230:233], 0
	v_mfma_f32_16x16x32_bf16 v[6:9], v[150:153], v[230:233], 0
	v_mfma_f32_16x16x32_bf16 v[58:61], v[158:161], v[206:209], 0
	v_mfma_f32_16x16x32_bf16 v[50:53], v[186:189], v[206:209], 0
	v_mfma_f32_16x16x32_bf16 v[42:45], v[158:161], v[214:217], 0
	v_mfma_f32_16x16x32_bf16 v[34:37], v[186:189], v[214:217], 0
	v_mfma_f32_16x16x32_bf16 v[26:29], v[158:161], v[222:225], 0
	v_mfma_f32_16x16x32_bf16 v[18:21], v[186:189], v[222:225], 0
	v_mfma_f32_16x16x32_bf16 v[10:13], v[158:161], v[230:233], 0
	v_mfma_f32_16x16x32_bf16 v[2:5], v[186:189], v[230:233], 0
	v_mfma_f32_16x16x32_bf16 v[62:65], v[146:149], v[210:213], v[62:65]
	v_mfma_f32_16x16x32_bf16 v[54:57], v[154:157], v[210:213], v[54:57]
	v_mfma_f32_16x16x32_bf16 v[46:49], v[146:149], v[218:221], v[46:49]
	v_mfma_f32_16x16x32_bf16 v[38:41], v[154:157], v[218:221], v[38:41]
	v_mfma_f32_16x16x32_bf16 v[30:33], v[146:149], v[226:229], v[30:33]
	v_mfma_f32_16x16x32_bf16 v[22:25], v[154:157], v[226:229], v[22:25]
	v_mfma_f32_16x16x32_bf16 v[14:17], v[146:149], v[234:237], v[14:17]
	v_mfma_f32_16x16x32_bf16 v[6:9], v[154:157], v[234:237], v[6:9]
	v_mfma_f32_16x16x32_bf16 v[58:61], v[178:181], v[210:213], v[58:61]
	v_mfma_f32_16x16x32_bf16 v[50:53], v[202:205], v[210:213], v[50:53]
	v_mfma_f32_16x16x32_bf16 v[42:45], v[178:181], v[218:221], v[42:45]
	v_mfma_f32_16x16x32_bf16 v[34:37], v[202:205], v[218:221], v[34:37]
	v_mfma_f32_16x16x32_bf16 v[26:29], v[178:181], v[226:229], v[26:29]
	v_mfma_f32_16x16x32_bf16 v[18:21], v[202:205], v[226:229], v[18:21]
	v_mfma_f32_16x16x32_bf16 v[10:13], v[178:181], v[234:237], v[10:13]
	v_mfma_f32_16x16x32_bf16 v[2:5], v[202:205], v[234:237], v[2:5]
	s_setprio 0
	s_barrier
	s_add_i32 s22, 0, 0x18000
	s_add_i32 s23, 0, 0x1c000
	v_add_u32_e32 v154, s22, v183
	v_add_u32_e32 v202, s23, v183
	ds_read_b128 v[130:133], v154
	ds_read_b128 v[146:149], v154 offset:1024
	ds_read_b128 v[150:153], v154 offset:2048
	ds_read_b128 v[154:157], v154 offset:3072
	ds_read_b128 v[158:161], v202
	ds_read_b128 v[178:181], v202 offset:1024
	ds_read_b128 v[186:189], v202 offset:2048
	ds_read_b128 v[202:205], v202 offset:3072
	s_add_u32 s14, s14, 0x40000
	s_addc_u32 s15, s15, 0
	s_mov_b32 m0, s40
	v_lshl_add_u64 v[242:243], s[14:15], 0, v[138:139]
	ds_read_b128 v[206:209], v185 offset:32768
	ds_read_b128 v[210:213], v185 offset:33792
	ds_read_b128 v[214:217], v185 offset:34816
	ds_read_b128 v[218:221], v185 offset:35840
	ds_read_b128 v[222:225], v185 offset:36864
	ds_read_b128 v[226:229], v185 offset:37888
	ds_read_b128 v[230:233], v185 offset:38912
	ds_read_b128 v[234:237], v185 offset:39936
	global_load_lds_dwordx4 v[242:243], off
	v_lshl_add_u64 v[242:243], s[14:15], 0, v[136:137]
	s_mov_b32 m0, s41
	s_nop 0
	global_load_lds_dwordx4 v[242:243], off
	s_waitcnt vmcnt(8)
	s_waitcnt lgkmcnt(0)
	s_barrier
	s_setprio 1
	s_waitcnt lgkmcnt(0)
	v_mfma_f32_16x16x32_bf16 v[126:129], v[130:133], v[206:209], v[126:129]
	v_mfma_f32_16x16x32_bf16 v[118:121], v[150:153], v[206:209], v[118:121]
	v_mfma_f32_16x16x32_bf16 v[110:113], v[130:133], v[214:217], v[110:113]
	v_mfma_f32_16x16x32_bf16 v[102:105], v[150:153], v[214:217], v[102:105]
	v_mfma_f32_16x16x32_bf16 v[94:97], v[130:133], v[222:225], v[94:97]
	v_mfma_f32_16x16x32_bf16 v[86:89], v[150:153], v[222:225], v[86:89]
	v_mfma_f32_16x16x32_bf16 v[78:81], v[130:133], v[230:233], v[78:81]
	v_mfma_f32_16x16x32_bf16 v[70:73], v[150:153], v[230:233], v[70:73]
	v_mfma_f32_16x16x32_bf16 v[122:125], v[158:161], v[206:209], v[122:125]
	v_mfma_f32_16x16x32_bf16 v[114:117], v[186:189], v[206:209], v[114:117]
	v_mfma_f32_16x16x32_bf16 v[106:109], v[158:161], v[214:217], v[106:109]
	v_mfma_f32_16x16x32_bf16 v[98:101], v[186:189], v[214:217], v[98:101]
	v_mfma_f32_16x16x32_bf16 v[90:93], v[158:161], v[222:225], v[90:93]
	v_mfma_f32_16x16x32_bf16 v[82:85], v[186:189], v[222:225], v[82:85]
	v_mfma_f32_16x16x32_bf16 v[74:77], v[158:161], v[230:233], v[74:77]
	v_mfma_f32_16x16x32_bf16 v[66:69], v[186:189], v[230:233], v[66:69]
	v_mfma_f32_16x16x32_bf16 v[126:129], v[146:149], v[210:213], v[126:129]
	v_mfma_f32_16x16x32_bf16 v[118:121], v[154:157], v[210:213], v[118:121]
	v_mfma_f32_16x16x32_bf16 v[110:113], v[146:149], v[218:221], v[110:113]
	v_mfma_f32_16x16x32_bf16 v[102:105], v[154:157], v[218:221], v[102:105]
	v_mfma_f32_16x16x32_bf16 v[94:97], v[146:149], v[226:229], v[94:97]
	v_mfma_f32_16x16x32_bf16 v[86:89], v[154:157], v[226:229], v[86:89]
	v_mfma_f32_16x16x32_bf16 v[78:81], v[146:149], v[234:237], v[78:81]
	v_mfma_f32_16x16x32_bf16 v[70:73], v[154:157], v[234:237], v[70:73]
	v_mfma_f32_16x16x32_bf16 v[122:125], v[178:181], v[210:213], v[122:125]
	v_mfma_f32_16x16x32_bf16 v[114:117], v[202:205], v[210:213], v[114:117]
	v_mfma_f32_16x16x32_bf16 v[106:109], v[178:181], v[218:221], v[106:109]
	v_mfma_f32_16x16x32_bf16 v[98:101], v[202:205], v[218:221], v[98:101]
	v_mfma_f32_16x16x32_bf16 v[90:93], v[178:181], v[226:229], v[90:93]
	v_mfma_f32_16x16x32_bf16 v[82:85], v[202:205], v[226:229], v[82:85]
	v_mfma_f32_16x16x32_bf16 v[74:77], v[178:181], v[234:237], v[74:77]
	v_mfma_f32_16x16x32_bf16 v[66:69], v[202:205], v[234:237], v[66:69]
	s_setprio 0
	s_barrier
; #define PG8_STAGE(bufoff, gbase, voff) do { _Pragma("unroll") for (int _i = 0; _i < 2; ++_i) \
;         __builtin_amdgcn_global_load_lds((const unsigned*)((const char*)(gbase) + (voff)[_i]), (PG8_LAS unsigned*)(lds + (bufoff) + ldsw + _i * 8192), 16, 0, 0); } while (0)
; #define PG8_LDA(dst, b, h) do { _Pragma("unroll") for (int m = 0; m < 4; ++m) _Pragma("unroll") for (int k = 0; k < 2; ++k) dst[m][k] = *(const PG8_LAS bf16x8*)(lds + PG8_SA(b, h) + aoff + m * 2048 + k * 1024); } while (0)
; #define PG8_MMA_NP(ai, bj, At, Bt) do { _Pragma("unroll") for (int m = 0; m < 4; ++m) _Pragma("unroll") for (int n = 0; n < 2; ++n) _Pragma("unroll") for (int k = 0; k < 2; ++k) \
;         acc[ai][bj][m][n] = __builtin_amdgcn_mfma_f32_16x16x32_bf16(Bt[n][k], At[m][k], acc[ai][bj][m][n], 0, 0, 0); } while (0)
; #define PG8_WAIT_V(n) asm volatile("s_waitcnt vmcnt(" #n ")" ::: "memory")
; #define PG8_WAIT_L(n) asm volatile("s_waitcnt lgkmcnt(" #n ")" ::: "memory")
; #define PG8_BAR __builtin_amdgcn_s_barrier()
; #define PG8_SCHED __builtin_amdgcn_sched_barrier(0)
; template <class Epi, class Sched, bool ALIGN_EPI = false, bool SP2 = false>
; __device__ __forceinline__ void gemm_phase(PG8_LAS unsigned char* lds, const Gemm g, const Sched& S, const Epi& E) {
;     ...
;         for (int t = 0; t < nt; t += 2) {
;     ...
;             PG8_LDA(At, 1, 1); PG8_STAGE(PG8_SB(1, 0), b3, voffB); PG8_STAGE(PG8_SB(1, 1), b3 + hstep, voffB); PG8_STAGE(PG8_SA(1, 0), a3, voffA);
;             PG8_WAIT_V(8); PG8_WAIT_L(0); PG8_BAR; __builtin_amdgcn_s_setprio(1); PG8_MMA_NP(1, 0, At, B0); PG8_MMA_NP(1, 1, At, B1); __builtin_amdgcn_s_setprio(0); PG8_BAR; PG8_SCHED;
	s_add_i32 s14, s22, s29
	v_lshl_add_u64 v[162:163], v[162:163], 0, s[20:21]
	s_mov_b32 m0, s14
	ds_read_b128 v[206:209], v185 offset:49152
	ds_read_b128 v[210:213], v185 offset:50176
	ds_read_b128 v[214:217], v185 offset:51200
	ds_read_b128 v[218:221], v185 offset:52224
	ds_read_b128 v[222:225], v185 offset:53248
	ds_read_b128 v[226:229], v185 offset:54272
	ds_read_b128 v[230:233], v185 offset:55296
	ds_read_b128 v[234:237], v185 offset:56320
	global_load_lds_dwordx4 v[162:163], off
	s_add_i32 m0, s14, 0x2000
	s_add_u32 s12, s12, 0x40080
	v_lshl_add_u64 v[162:163], v[190:191], 0, s[20:21]
	s_addc_u32 s13, s13, 0
	s_add_i32 s14, s23, s29
	global_load_lds_dwordx4 v[162:163], off
	v_lshl_add_u64 v[162:163], s[12:13], 0, v[0:1]
	s_mov_b32 m0, s14
	s_nop 0
	global_load_lds_dwordx4 v[162:163], off
	v_lshl_add_u64 v[162:163], s[12:13], 0, v[134:135]
	s_add_i32 m0, s14, 0x2000
	s_nop 0
	global_load_lds_dwordx4 v[162:163], off
	v_lshl_add_u64 v[162:163], v[238:239], 0, s[20:21]
	s_mov_b32 m0, s54
	s_nop 0
	global_load_lds_dwordx4 v[162:163], off
	v_lshl_add_u64 v[162:163], v[240:241], 0, s[20:21]
	s_mov_b32 m0, s55
	s_nop 0
	global_load_lds_dwordx4 v[162:163], off
	s_waitcnt vmcnt(8)
	s_waitcnt lgkmcnt(0)
	s_barrier
	s_setprio 1
	s_waitcnt lgkmcnt(0)
	v_mfma_f32_16x16x32_bf16 v[62:65], v[130:133], v[206:209], v[62:65]
	v_mfma_f32_16x16x32_bf16 v[54:57], v[150:153], v[206:209], v[54:57]
	v_mfma_f32_16x16x32_bf16 v[46:49], v[130:133], v[214:217], v[46:49]
	v_mfma_f32_16x16x32_bf16 v[38:41], v[150:153], v[214:217], v[38:41]
	v_mfma_f32_16x16x32_bf16 v[30:33], v[130:133], v[222:225], v[30:33]
	v_mfma_f32_16x16x32_bf16 v[22:25], v[150:153], v[222:225], v[22:25]
	v_mfma_f32_16x16x32_bf16 v[14:17], v[130:133], v[230:233], v[14:17]
	v_mfma_f32_16x16x32_bf16 v[6:9], v[150:153], v[230:233], v[6:9]
	v_mfma_f32_16x16x32_bf16 v[58:61], v[158:161], v[206:209], v[58:61]
	v_mfma_f32_16x16x32_bf16 v[50:53], v[186:189], v[206:209], v[50:53]
	v_mfma_f32_16x16x32_bf16 v[42:45], v[158:161], v[214:217], v[42:45]
	v_mfma_f32_16x16x32_bf16 v[34:37], v[186:189], v[214:217], v[34:37]
	v_mfma_f32_16x16x32_bf16 v[26:29], v[158:161], v[222:225], v[26:29]
	v_mfma_f32_16x16x32_bf16 v[18:21], v[186:189], v[222:225], v[18:21]
	v_mfma_f32_16x16x32_bf16 v[10:13], v[158:161], v[230:233], v[10:13]
	v_mfma_f32_16x16x32_bf16 v[2:5], v[186:189], v[230:233], v[2:5]
	v_mfma_f32_16x16x32_bf16 v[62:65], v[146:149], v[210:213], v[62:65]
	v_mfma_f32_16x16x32_bf16 v[54:57], v[154:157], v[210:213], v[54:57]
	v_mfma_f32_16x16x32_bf16 v[46:49], v[146:149], v[218:221], v[46:49]
	v_mfma_f32_16x16x32_bf16 v[38:41], v[154:157], v[218:221], v[38:41]
	v_mfma_f32_16x16x32_bf16 v[30:33], v[146:149], v[226:229], v[30:33]
	v_mfma_f32_16x16x32_bf16 v[22:25], v[154:157], v[226:229], v[22:25]
	v_mfma_f32_16x16x32_bf16 v[14:17], v[146:149], v[234:237], v[14:17]
	v_mfma_f32_16x16x32_bf16 v[6:9], v[154:157], v[234:237], v[6:9]
	v_mfma_f32_16x16x32_bf16 v[58:61], v[178:181], v[210:213], v[58:61]
	v_mfma_f32_16x16x32_bf16 v[50:53], v[202:205], v[210:213], v[50:53]
	v_mfma_f32_16x16x32_bf16 v[42:45], v[178:181], v[218:221], v[42:45]
	v_mfma_f32_16x16x32_bf16 v[34:37], v[202:205], v[218:221], v[34:37]
	v_mfma_f32_16x16x32_bf16 v[26:29], v[178:181], v[226:229], v[26:29]
	v_mfma_f32_16x16x32_bf16 v[18:21], v[202:205], v[226:229], v[18:21]
	v_mfma_f32_16x16x32_bf16 v[10:13], v[178:181], v[234:237], v[10:13]
	v_mfma_f32_16x16x32_bf16 v[2:5], v[202:205], v[234:237], v[2:5]
	s_setprio 0
	s_barrier
	s_add_i32 s63, s63, 2
	s_add_u32 s2, s2, 0x100
	s_addc_u32 s3, s3, 0
	s_add_u32 s61, s61, 0x100
	s_addc_u32 s62, s62, 0
	s_cmp_gt_u32 s63, 13
	s_cbranch_scc0 .LBB0_1122
	s_branch .Lkexit_5
	.p2align 3

; #define PG8_BAR __builtin_amdgcn_s_barrier()
; template <class Epi, class Sched, bool ALIGN_EPI = false, bool SP2 = false>
; __device__ __forceinline__ void gemm_phase(PG8_LAS unsigned char* lds, const Gemm g, const Sched& S, const Epi& E) {
;     ...
;         if constexpr (ALIGN_EPI) { if (wr == 0) PG8_BAR; }
;     DI void operator()(const f32x4 (&acc)[2][2][4][2], const pg8::Unit& u, int wr, int wc, int fr, int fq) const {
;         const int row0 = u.pm * 256 + wr * 64 + fr, col0 = u.pn * 128 + wc * 32 + 8 * fq;
;         float rs[2][4]; row_rstd(ssq, row0, fq, rs);
; #pragma unroll
;         for (int ai = 0; ai < 2; ++ai)
; #pragma unroll
;             for (int m = 0; m < 4; ++m) {
;                 typedef float f32x2 __attribute__((ext_vector_type(2)));
;                 const float r = rs[ai][m]; const float r2s = r * r, rls = r * -1.44269504f; const f32x2 r2 = {r2s, r2s}, rl = {rls, rls};
.Lrc_skip_1:
	s_and_b64 vcc, exec, s[44:45]
	s_cbranch_vccz .LBB0_1125
	s_barrier
.LBB0_1125:
	v_and_b32_e32 v131, 64, v194
	v_xor_b32_e32 v130, 16, v194
	v_add_u32_e32 v131, 64, v131
	v_cmp_lt_i32_e32 vcc, v130, v131
	v_lshl_add_u32 v160, s58, 8, v182
	v_ashrrev_i32_e32 v161, 31, v160
	v_cndmask_b32_e32 v130, v194, v130, vcc
	v_lshlrev_b32_e32 v186, 2, v130
	v_xor_b32_e32 v130, 32, v194
	v_cmp_lt_i32_e32 vcc, v130, v131
	v_or_b32_e32 v158, 16, v160
	v_ashrrev_i32_e32 v159, 31, v158
	v_cndmask_b32_e32 v130, v194, v130, vcc
	v_lshlrev_b32_e32 v163, 2, v130
	v_lshlrev_b64 v[130:131], 6, v[160:161]
	v_lshl_add_u64 v[130:131], v[140:141], 0, v[130:131]
	v_mov_b64_e32 v[178:179], s[16:17]
	v_or_b32_e32 v156, 32, v160
	v_ashrrev_i32_e32 v157, 31, v156
	v_or_b32_e32 v154, 48, v160
	v_ashrrev_i32_e32 v155, 31, v154
	v_add_u32_e32 v152, 0x80, v160
	v_ashrrev_i32_e32 v153, 31, v152
	v_add_u32_e32 v150, 0x90, v160
	v_ashrrev_i32_e32 v151, 31, v150
	v_pk_mul_f32 v[122:123], v[126:127], v[122:123]
	v_pk_mul_f32 v[124:125], v[128:129], v[124:125]
	v_pk_mul_f32 v[114:115], v[118:119], v[114:115]
	v_pk_mul_f32 v[116:117], v[120:121], v[116:117]
	v_lshl_or_b32 v162, s57, 7, v184
	v_pk_mul_f32 v[106:107], v[110:111], v[106:107]
	v_pk_mul_f32 v[108:109], v[112:113], v[108:109]
	v_pk_mul_f32 v[98:99], v[102:103], v[98:99]
	v_pk_mul_f32 v[100:101], v[104:105], v[100:101]
	v_pk_mul_f32 v[90:91], v[94:95], v[90:91]
	v_pk_mul_f32 v[92:93], v[96:97], v[92:93]
	v_pk_mul_f32 v[82:83], v[86:87], v[82:83]
	v_pk_mul_f32 v[84:85], v[88:89], v[84:85]
	v_pk_mul_f32 v[74:75], v[78:79], v[74:75]
	v_pk_mul_f32 v[76:77], v[80:81], v[76:77]
	v_pk_mul_f32 v[66:67], v[70:71], v[66:67]
	v_pk_mul_f32 v[68:69], v[72:73], v[68:69]
	v_pk_mul_f32 v[58:59], v[62:63], v[58:59]
	v_pk_mul_f32 v[60:61], v[64:65], v[60:61]
	v_pk_mul_f32 v[50:51], v[54:55], v[50:51]
	v_pk_mul_f32 v[52:53], v[56:57], v[52:53]
	v_pk_mul_f32 v[42:43], v[46:47], v[42:43]
	v_pk_mul_f32 v[44:45], v[48:49], v[44:45]
	v_pk_mul_f32 v[34:35], v[38:39], v[34:35]
	v_pk_mul_f32 v[36:37], v[40:41], v[36:37]
	v_pk_mul_f32 v[26:27], v[30:31], v[26:27]
	v_pk_mul_f32 v[28:29], v[32:33], v[28:29]
	v_pk_mul_f32 v[18:19], v[22:23], v[18:19]
	v_pk_mul_f32 v[20:21], v[24:25], v[20:21]
	v_pk_mul_f32 v[10:11], v[14:15], v[10:11]
	v_pk_mul_f32 v[12:13], v[16:17], v[12:13]
	v_pk_mul_f32 v[2:3], v[6:7], v[2:3]
	v_pk_mul_f32 v[4:5], v[8:9], v[4:5]
	s_cmp_eq_u32 s58, s98
	s_cbranch_scc1 .Lrc_hit_1
; DI void row_rstd(const float* ssq, int row0, int fq, float (&rs)[2][4]) {
;     ...
;             const f32x4 v = *(const f32x4*)(ssq + (size_t)(row0 + ai * 128 + m * 16) * 16 + 4 * fq);
;             float s = (v[0] + v[1]) + (v[2] + v[3]);
;             s += __shfl_xor(s, 16); s += __shfl_xor(s, 32);
;             rs[ai][m] = rsqrtf(s * (1.0f / DM) + EPS);
	s_waitcnt vmcnt(7)
	v_mov_b32_e32 v130, v202
	v_mov_b32_e32 v131, v203
	v_mov_b32_e32 v132, v204
	v_mov_b32_e32 v133, v205
	v_mov_b32_e32 v146, v131
	v_mov_b32_e32 v147, v132
	v_mov_b32_e32 v131, v133
	v_pk_add_f32 v[146:147], v[146:147], v[130:131]
	v_lshlrev_b64 v[130:131], 6, v[158:159]
	v_lshl_add_u64 v[130:131], v[140:141], 0, v[130:131]
	s_waitcnt vmcnt(6)
	v_mov_b32_e32 v130, v206
	v_mov_b32_e32 v131, v207
	v_mov_b32_e32 v132, v208
	v_mov_b32_e32 v133, v209
	v_mov_b32_e32 v148, v131
	v_mov_b32_e32 v149, v132
	v_mov_b32_e32 v131, v133
	v_pk_add_f32 v[130:131], v[148:149], v[130:131]
	v_mov_b32_e32 v133, v146
	v_mov_b32_e32 v132, v130
	v_mov_b32_e32 v146, v131
	v_pk_add_f32 v[130:131], v[132:133], v[146:147]
	ds_bpermute_b32 v133, v186, v131
	ds_bpermute_b32 v132, v186, v130
	s_waitcnt lgkmcnt(0)
	v_pk_add_f32 v[130:131], v[130:131], v[132:133]
	ds_bpermute_b32 v133, v163, v131
	ds_bpermute_b32 v132, v163, v130
	s_waitcnt lgkmcnt(0)
	v_pk_add_f32 v[130:131], v[130:131], v[132:133]
	s_nop 0
	v_pk_fma_f32 v[130:131], v[130:131], s[34:35], v[178:179] op_sel_hi:[1,0,0]
	s_nop 0
	v_mul_f32_e32 v132, 0x4b800000, v131
	v_cmp_gt_f32_e64 s[2:3], s25, v131
	v_cmp_gt_f32_e32 vcc, s25, v130
	s_nop 0
	v_cndmask_b32_e64 v131, v131, v132, s[2:3]
	v_rsq_f32_e32 v131, v131
	s_nop 0
	v_mul_f32_e32 v132, 0x45800000, v131
	v_cndmask_b32_e64 v161, v131, v132, s[2:3]
	v_mul_f32_e32 v131, 0x4b800000, v130
	v_cndmask_b32_e32 v130, v130, v131, vcc
	v_rsq_f32_e32 v130, v130
	s_nop 0
	v_mul_f32_e32 v131, 0x45800000, v130
	v_cndmask_b32_e32 v159, v130, v131, vcc
	v_lshlrev_b64 v[130:131], 6, v[156:157]
	v_lshl_add_u64 v[130:131], v[140:141], 0, v[130:131]
	s_waitcnt vmcnt(5)
	v_mov_b32_e32 v130, v210
	v_mov_b32_e32 v131, v211
	v_mov_b32_e32 v132, v212
	v_mov_b32_e32 v133, v213
	v_mov_b32_e32 v146, v131
	v_mov_b32_e32 v147, v132
	v_mov_b32_e32 v131, v133
	v_pk_add_f32 v[146:147], v[146:147], v[130:131]
	v_lshlrev_b64 v[130:131], 6, v[154:155]
	v_lshl_add_u64 v[130:131], v[140:141], 0, v[130:131]
	s_waitcnt vmcnt(4)
	v_mov_b32_e32 v130, v214
	v_mov_b32_e32 v131, v215
	v_mov_b32_e32 v132, v216
	v_mov_b32_e32 v133, v217
	v_mov_b32_e32 v148, v131
	v_mov_b32_e32 v149, v132
	v_mov_b32_e32 v131, v133
	v_pk_add_f32 v[130:131], v[148:149], v[130:131]
	v_mov_b32_e32 v133, v146
	v_mov_b32_e32 v132, v130
	v_mov_b32_e32 v146, v131
	v_pk_add_f32 v[130:131], v[132:133], v[146:147]
	ds_bpermute_b32 v133, v186, v131
	ds_bpermute_b32 v132, v186, v130
	s_waitcnt lgkmcnt(0)
	v_pk_add_f32 v[130:131], v[130:131], v[132:133]
	ds_bpermute_b32 v133, v163, v131
	ds_bpermute_b32 v132, v163, v130
	s_waitcnt lgkmcnt(0)
	v_pk_add_f32 v[130:131], v[130:131], v[132:133]
	s_nop 0
	v_pk_fma_f32 v[130:131], v[130:131], s[34:35], v[178:179] op_sel_hi:[1,0,0]
	s_nop 0
	v_mul_f32_e32 v132, 0x4b800000, v131
	v_cmp_gt_f32_e64 s[2:3], s25, v131
	v_cmp_gt_f32_e32 vcc, s25, v130
	s_nop 0
	v_cndmask_b32_e64 v131, v131, v132, s[2:3]
	v_rsq_f32_e32 v131, v131
	s_nop 0
	v_mul_f32_e32 v132, 0x45800000, v131
	v_cndmask_b32_e64 v157, v131, v132, s[2:3]
	v_mul_f32_e32 v131, 0x4b800000, v130
	v_cndmask_b32_e32 v130, v130, v131, vcc
	v_rsq_f32_e32 v130, v130
	s_nop 0
	v_mul_f32_e32 v131, 0x45800000, v130
	v_cndmask_b32_e32 v155, v130, v131, vcc
	v_lshlrev_b64 v[130:131], 6, v[152:153]
	v_lshl_add_u64 v[130:131], v[140:141], 0, v[130:131]
	s_waitcnt vmcnt(3)
	v_mov_b32_e32 v130, v218
	v_mov_b32_e32 v131, v219
	v_mov_b32_e32 v132, v220
	v_mov_b32_e32 v133, v221
	v_mov_b32_e32 v146, v131
	v_mov_b32_e32 v147, v132
	v_mov_b32_e32 v131, v133
	v_pk_add_f32 v[146:147], v[146:147], v[130:131]
	v_lshlrev_b64 v[130:131], 6, v[150:151]
	v_lshl_add_u64 v[130:131], v[140:141], 0, v[130:131]
	s_waitcnt vmcnt(2)
	v_mov_b32_e32 v130, v222
	v_mov_b32_e32 v131, v223
	v_mov_b32_e32 v132, v224
	v_mov_b32_e32 v133, v225
	v_mov_b32_e32 v148, v131
	v_mov_b32_e32 v149, v132
	v_mov_b32_e32 v131, v133
	v_pk_add_f32 v[130:131], v[148:149], v[130:131]
	v_mov_b32_e32 v133, v146
	v_mov_b32_e32 v132, v130
	v_mov_b32_e32 v146, v131
	v_pk_add_f32 v[130:131], v[132:133], v[146:147]
	ds_bpermute_b32 v133, v186, v131
	ds_bpermute_b32 v132, v186, v130
	v_add_u32_e32 v148, 0xa0, v160
	v_ashrrev_i32_e32 v149, 31, v148
	s_waitcnt lgkmcnt(0)
	v_pk_add_f32 v[130:131], v[130:131], v[132:133]
	ds_bpermute_b32 v133, v163, v131
	ds_bpermute_b32 v132, v163, v130
	s_waitcnt lgkmcnt(0)
	v_pk_add_f32 v[130:131], v[130:131], v[132:133]
	s_nop 0
	v_pk_fma_f32 v[130:131], v[130:131], s[34:35], v[178:179] op_sel_hi:[1,0,0]
	s_nop 0
	v_mul_f32_e32 v132, 0x4b800000, v131
	v_cmp_gt_f32_e64 s[2:3], s25, v131
	v_cmp_gt_f32_e32 vcc, s25, v130
	s_nop 0
	v_cndmask_b32_e64 v131, v131, v132, s[2:3]
	v_rsq_f32_e32 v131, v131
	s_nop 0
	v_mul_f32_e32 v132, 0x45800000, v131
	v_cndmask_b32_e64 v153, v131, v132, s[2:3]
	v_mul_f32_e32 v131, 0x4b800000, v130
	v_cndmask_b32_e32 v130, v130, v131, vcc
	v_rsq_f32_e32 v130, v130
	s_nop 0
	v_mul_f32_e32 v131, 0x45800000, v130
	v_cndmask_b32_e32 v151, v130, v131, vcc
	v_lshlrev_b64 v[130:131], 6, v[148:149]
	v_lshl_add_u64 v[130:131], v[140:141], 0, v[130:131]
	v_accvgpr_write_b32 a0, v161
	v_accvgpr_write_b32 a1, v159
	v_accvgpr_write_b32 a2, v157
	v_accvgpr_write_b32 a3, v155
	v_accvgpr_write_b32 a4, v153
	v_accvgpr_write_b32 a5, v151
	s_waitcnt vmcnt(1)
	v_mov_b32_e32 v130, v226
	v_mov_b32_e32 v131, v227
	v_mov_b32_e32 v132, v228
	v_mov_b32_e32 v133, v229
	v_mov_b32_e32 v146, v131
	v_mov_b32_e32 v147, v132
	v_mov_b32_e32 v131, v133
	v_pk_add_f32 v[180:181], v[146:147], v[130:131]
	v_add_u32_e32 v146, 0xb0, v160
	v_ashrrev_i32_e32 v147, 31, v146
	v_lshlrev_b64 v[130:131], 6, v[146:147]
	v_lshl_add_u64 v[130:131], v[140:141], 0, v[130:131]
	s_waitcnt vmcnt(0)
	v_mov_b32_e32 v130, v230
	v_mov_b32_e32 v131, v231
	v_mov_b32_e32 v132, v232
	v_mov_b32_e32 v133, v233
	v_mov_b32_e32 v188, v131
	v_mov_b32_e32 v189, v132
	v_mov_b32_e32 v131, v133
	v_pk_add_f32 v[130:131], v[188:189], v[130:131]
	v_mov_b32_e32 v133, v180
	v_mov_b32_e32 v132, v130
	v_mov_b32_e32 v180, v131
	v_pk_add_f32 v[130:131], v[132:133], v[180:181]
	ds_bpermute_b32 v133, v186, v131
	ds_bpermute_b32 v132, v186, v130
	s_waitcnt lgkmcnt(0)
	v_pk_add_f32 v[130:131], v[130:131], v[132:133]
	ds_bpermute_b32 v133, v163, v131
	ds_bpermute_b32 v132, v163, v130
	v_ashrrev_i32_e32 v163, 31, v162
	s_waitcnt lgkmcnt(0)
	v_pk_add_f32 v[130:131], v[130:131], v[132:133]
	s_nop 0
	v_pk_fma_f32 v[130:131], v[130:131], s[34:35], v[178:179] op_sel_hi:[1,0,0]
	v_mul_f32_e32 v132, 0x4b800000, v131
	v_cmp_gt_f32_e64 s[2:3], s25, v131
	s_nop 1
	v_cndmask_b32_e64 v131, v131, v132, s[2:3]
	v_rsq_f32_e32 v131, v131
	s_nop 0
	v_cmp_gt_f32_e32 vcc, s25, v130
	v_mul_f32_e32 v132, 0x45800000, v131
	v_cndmask_b32_e64 v131, v131, v132, s[2:3]
	v_mul_f32_e32 v132, 0x4b800000, v130
	v_cndmask_b32_e32 v130, v130, v132, vcc
	v_rsq_f32_e32 v130, v130
	s_nop 0
	v_mul_f32_e32 v132, 0x45800000, v130
	v_cndmask_b32_e32 v130, v130, v132, vcc
	v_accvgpr_write_b32 a6, v131
	v_accvgpr_write_b32 a7, v130
	s_mov_b32 s98, s58
	s_branch .Lrc_done_1

; template <class Epi, class Sched, bool ALIGN_EPI = false, bool SP2 = false>
; __device__ __forceinline__ void gemm_phase(PG8_LAS unsigned char* lds, const Gemm g, const Sched& S, const Epi& E) {
;     ...
; #pragma unroll
;         for (int a = 0; a < 2; ++a)
; #pragma unroll
;             for (int b = 0; b < 2; ++b)
; #pragma unroll
;                 for (int m = 0; m < 4; ++m)
; #pragma unroll
;                     for (int n = 0; n < 2; ++n) acc[a][b][m][n] = (f32x4){0.f, 0.f, 0.f, 0.f};
.LBB0_1219:
	s_add_u32 s62, s48, 0x100
	v_mov_b32_e32 v2, 0
	s_addc_u32 s63, s49, 0
	s_mov_b32 s64, -2
	s_waitcnt lgkmcnt(0)
	v_mov_b32_e32 v3, v2
	v_mov_b32_e32 v4, v2
	v_mov_b32_e32 v5, v2
	v_mov_b32_e32 v6, v2
	v_mov_b32_e32 v7, v2
	v_mov_b32_e32 v8, v2
	v_mov_b32_e32 v9, v2
	v_mov_b32_e32 v18, v2
	v_mov_b32_e32 v19, v2
	v_mov_b32_e32 v20, v2
	v_mov_b32_e32 v21, v2
	v_mov_b32_e32 v22, v2
	v_mov_b32_e32 v23, v2
	v_mov_b32_e32 v24, v2
	v_mov_b32_e32 v25, v2
	v_mov_b32_e32 v34, v2
	v_mov_b32_e32 v35, v2
	v_mov_b32_e32 v36, v2
	v_mov_b32_e32 v37, v2
	v_mov_b32_e32 v38, v2
	v_mov_b32_e32 v39, v2
	v_mov_b32_e32 v40, v2
	v_mov_b32_e32 v41, v2
	v_mov_b32_e32 v50, v2
	v_mov_b32_e32 v51, v2
	v_mov_b32_e32 v52, v2
	v_mov_b32_e32 v53, v2
	v_mov_b32_e32 v54, v2
	v_mov_b32_e32 v55, v2
	v_mov_b32_e32 v56, v2
	v_mov_b32_e32 v57, v2
	v_mov_b32_e32 v10, v2
	v_mov_b32_e32 v11, v2
	v_mov_b32_e32 v12, v2
	v_mov_b32_e32 v13, v2
	v_mov_b32_e32 v14, v2
	v_mov_b32_e32 v15, v2
	v_mov_b32_e32 v16, v2
	v_mov_b32_e32 v17, v2
	v_mov_b32_e32 v26, v2
	v_mov_b32_e32 v27, v2
	v_mov_b32_e32 v28, v2
	v_mov_b32_e32 v29, v2
	v_mov_b32_e32 v30, v2
	v_mov_b32_e32 v31, v2
	v_mov_b32_e32 v32, v2
	v_mov_b32_e32 v33, v2
	v_mov_b32_e32 v42, v2
	v_mov_b32_e32 v43, v2
	v_mov_b32_e32 v44, v2
	v_mov_b32_e32 v45, v2
	v_mov_b32_e32 v46, v2
	v_mov_b32_e32 v47, v2
	v_mov_b32_e32 v48, v2
	v_mov_b32_e32 v49, v2
	v_mov_b32_e32 v58, v2
	v_mov_b32_e32 v59, v2
	v_mov_b32_e32 v60, v2
	v_mov_b32_e32 v61, v2
	v_mov_b32_e32 v62, v2
	v_mov_b32_e32 v63, v2
	v_mov_b32_e32 v64, v2
	v_mov_b32_e32 v65, v2
	v_mov_b32_e32 v66, v2
	v_mov_b32_e32 v67, v2
	v_mov_b32_e32 v68, v2
	v_mov_b32_e32 v69, v2
	v_mov_b32_e32 v70, v2
	v_mov_b32_e32 v71, v2
	v_mov_b32_e32 v72, v2
	v_mov_b32_e32 v73, v2
	v_mov_b32_e32 v82, v2
	v_mov_b32_e32 v83, v2
	v_mov_b32_e32 v84, v2
	v_mov_b32_e32 v85, v2
	v_mov_b32_e32 v86, v2
	v_mov_b32_e32 v87, v2
	v_mov_b32_e32 v88, v2
	v_mov_b32_e32 v89, v2
	v_mov_b32_e32 v98, v2
	v_mov_b32_e32 v99, v2
	v_mov_b32_e32 v100, v2
	v_mov_b32_e32 v101, v2
	v_mov_b32_e32 v102, v2
	v_mov_b32_e32 v103, v2
	v_mov_b32_e32 v104, v2
	v_mov_b32_e32 v105, v2
	v_mov_b32_e32 v114, v2
	v_mov_b32_e32 v115, v2
	v_mov_b32_e32 v116, v2
	v_mov_b32_e32 v117, v2
	v_mov_b32_e32 v118, v2
	v_mov_b32_e32 v119, v2
	v_mov_b32_e32 v120, v2
	v_mov_b32_e32 v121, v2
	v_mov_b32_e32 v74, v2
	v_mov_b32_e32 v75, v2
	v_mov_b32_e32 v76, v2
	v_mov_b32_e32 v77, v2
	v_mov_b32_e32 v78, v2
	v_mov_b32_e32 v79, v2
	v_mov_b32_e32 v80, v2
	v_mov_b32_e32 v81, v2
	v_mov_b32_e32 v90, v2
	v_mov_b32_e32 v91, v2
	v_mov_b32_e32 v92, v2
	v_mov_b32_e32 v93, v2
	v_mov_b32_e32 v94, v2
	v_mov_b32_e32 v95, v2
	v_mov_b32_e32 v96, v2
	v_mov_b32_e32 v97, v2
	v_mov_b32_e32 v106, v2
	v_mov_b32_e32 v107, v2
	v_mov_b32_e32 v108, v2
	v_mov_b32_e32 v109, v2
	v_mov_b32_e32 v110, v2
	v_mov_b32_e32 v111, v2
	v_mov_b32_e32 v112, v2
	v_mov_b32_e32 v113, v2
	v_mov_b32_e32 v122, v2
	v_mov_b32_e32 v123, v2
	v_mov_b32_e32 v124, v2
	v_mov_b32_e32 v125, v2
	v_mov_b32_e32 v126, v2
	v_mov_b32_e32 v127, v2
	v_mov_b32_e32 v128, v2
	v_mov_b32_e32 v129, v2
	.p2align 3
